# v11 + counted lgkmcnt waits in attention QK stream + two-pass weight-conversion split (WGs with an extra GEMM tile convert fewer items) in the mLSTM-in and MLA-in phases
# speedup vs baseline: 1.0050x; 1.0050x over previous
; #define LAS __attribute__((address_space(3)))
; __device__ __forceinline__ int opaque_tid() { int t = threadIdx.x; asm volatile("" : "+v"(t)); return t; }
; #define CONV_FFN(wgu_, wd_, norm_, layer, WGU_, WD_) do { for (int rep_ = 0; rep_ < REP_CONV; ++rep_) { \
;         conv_matrix((wgu_) + (size_t)(layer) * D * 2 * FF, D, 2 * FF, 0, 2 * FF, (WGU_), 0, 1, (norm_) + (layer) * D, lds); \
;         conv_matrix((wd_) + (size_t)(layer) * FF * D, FF, D, 0, D, (WD_), 0, 0, nullptr, lds); } \
;         __syncthreads();   } while (0)
; __device__ __forceinline__ void conv_matrix(const float* W, int K, int ldn, int c0, int ncols, bf16_t* WT, int drow0, int mode, const float* gain, LAS unsigned char* lds) {
;     const int tid = opaque_tid(), lane = tid & 63, wave = __builtin_amdgcn_readfirstlane(tid >> 6), gw = blockIdx.x * NWAVES + wave, ngw = gridDim.x * NWAVES;
;     LAS float* scr = (LAS float*)(lds + wave * 16384);
;     const int nblk = ncols / 32, nitems = (K / 64) * nblk;
;     for (int it = gw; it < nitems; it += ngw) {
;         const int kb = it / nblk, nb = it - kb * nblk, k0 = 64 * kb, n0 = c0 + 32 * nb;
;         int drow;
;         if (mode == 1) { const int up = n0 >= FF ? 1 : 0, j = n0 - up * FF; drow = (j >> 7) * 256 + up * 128 + (j & 127); } else drow = drow0 + 32 * nb;
; #pragma unroll 8
;         for (int i = 0; i < 32; ++i) { const int kk = 2 * i + (lane >> 5); scr[kk * 33 + (lane & 31)] = W[(size_t)(k0 + kk) * ldn + n0 + (lane & 31)]; }
;         asm volatile("s_waitcnt lgkmcnt(0)" ::: "memory");
;         const int c = lane & 7;
;         f32x4 g0 = {1.f, 1.f, 1.f, 1.f}, g1 = {1.f, 1.f, 1.f, 1.f};
;         if (gain) { g0 = *(const f32x4*)(gain + k0 + 8 * c); g1 = *(const f32x4*)(gain + k0 + 8 * c + 4); }
; __global__ void __launch_bounds__(NWAVES * 64, 2) mega_fwd(Args a) {
;     ...
;     CONV_FFN(a.ffn1_wgu, a.ffn1_wd, a.ffn1_norm, 0, WGU, WD);
;     conv_matrix(a.ml_win, D, 6152, 0, 2048, WMIA, 0, 0, a.mix_norm, lds);
.LBB0_425:
	s_or_b64 exec, exec, s[0:1]
	s_waitcnt lgkmcnt(0)
	s_barrier
	s_mov_b32 s101, 0
.Lcv_p1a_top:
	v_mov_b32_e32 v0, v204
	s_nop 0
	v_readfirstlane_b32 s0, v0
	s_ashr_i32 s4, s0, 6
	s_add_i32 s8, s4, s97
	s_mov_b32 s98, s72
	s_movk_i32 s99, 0x2c00
	s_cmp_lg_u32 s72, 0x800
	s_cbranch_scc1 .Lcv_p1a_go
	s_cmp_eq_u32 s101, 0
	s_cbranch_scc0 .Lcv_p1a_second
	s_movk_i32 s99, 4096
	s_branch .Lcv_p1a_go
.Lcv_p1a_second:
	s_add_i32 s8, s8, 3584
	s_movk_i32 s98, 0x600
.Lcv_p1a_go:
	s_cmp_lt_i32 s8, s99
	s_cbranch_scc0 .Lcv_p1a_exit
	s_cmp_lg_u64 s[68:69], 0
	s_cselect_b64 s[0:1], -1, 0
	s_lshl_b32 s4, s4, 14
	v_lshlrev_b32_e32 v1, 2, v0
	s_add_i32 s4, s4, 0
	v_and_b32_e32 v2, 0x7c, v1
	v_mov_b32_e32 v3, 0
	v_and_b32_e32 v1, 7, v0
	s_waitcnt vmcnt(0)
	v_lshl_add_u64 v[10:11], s[70:71], 0, v[2:3]
	v_add_u32_e32 v12, s4, v2
	v_lshlrev_b32_e32 v2, 5, v1
	v_bfe_u32 v13, v0, 3, 3
	v_bfe_u32 v8, v0, 5, 1
	v_lshl_add_u64 v[14:15], s[68:69], 0, v[2:3]
	v_mul_u32_u24_e32 v0, 0x420, v1
	v_lshlrev_b32_e32 v2, 4, v1
	v_lshlrev_b32_e32 v1, 2, v13
	v_lshl_add_u64 v[16:17], s[78:79], 0, v[2:3]
	v_add3_u32 v20, s4, v0, v1
	v_or_b32_e32 v21, 8, v13
	v_or_b32_e32 v22, 16, v13
	v_or_b32_e32 v23, 24, v13
	v_mov_b32_e32 v9, v8
	s_mov_b32 s9, 0xb000
	s_movk_i32 s10, 0x84
	s_movk_i32 s11, 0x7fff
	s_mov_b32 s12, 0xffff0000
	s_branch .LBB0_429

; #define LAS __attribute__((address_space(3)))
; __device__ __forceinline__ unsigned pk2(float lo, float hi) { return f2bf(lo) | (f2bf(hi) << 16); }
; __device__ __forceinline__ void conv_matrix(const float* W, int K, int ldn, int c0, int ncols, bf16_t* WT, int drow0, int mode, const float* gain, LAS unsigned char* lds) {
;     ...
;         const int c = lane & 7;
;         f32x4 g0 = {1.f, 1.f, 1.f, 1.f}, g1 = {1.f, 1.f, 1.f, 1.f};
;         if (gain) { g0 = *(const f32x4*)(gain + k0 + 8 * c); g1 = *(const f32x4*)(gain + k0 + 8 * c + 4); }
; #pragma unroll
;         for (int j = 0; j < 4; ++j) { const int n = (lane >> 3) + 8 * j; const LAS float* s = scr + (8 * c) * 33 + n;
;             u32x4 o; o.x = pk2(s[0 * 33] * g0.x, s[1 * 33] * g0.y); o.y = pk2(s[2 * 33] * g0.z, s[3 * 33] * g0.w); o.z = pk2(s[4 * 33] * g1.x, s[5 * 33] * g1.y); o.w = pk2(s[6 * 33] * g1.z, s[7 * 33] * g1.w);
;             *(u32x4*)(WT + (size_t)(drow + n) * K + k0 + 8 * c) = o; }
;         asm volatile("s_waitcnt lgkmcnt(0)" ::: "memory");
;     }
.LBB0_428:
	ds_read2_b32 v[6:7], v20 offset1:8
	ds_read2_b32 v[28:29], v20 offset0:66 offset1:74
	ds_read2_b32 v[32:33], v20 offset0:33 offset1:41
	ds_read2_b32 v[34:35], v20 offset0:99 offset1:107
	ds_read2_b32 v[36:37], v20 offset0:132 offset1:140
	ds_read2_b32 v[38:39], v20 offset0:198 offset1:206
	ds_read2_b32 v[40:41], v20 offset0:165 offset1:173
	ds_read2_b32 v[42:43], v20 offset0:231 offset1:239
	s_cmpk_gt_i32 s13, 0xaf
	s_cselect_b32 s7, 0xffffea00, 0
	s_cselect_b32 s13, 0x80, 0
	s_add_i32 s7, s7, s6
	s_waitcnt lgkmcnt(5)
	v_mov_b32_e32 v26, v32
	s_waitcnt lgkmcnt(4)
	v_mov_b32_e32 v27, v34
	s_waitcnt lgkmcnt(3)
	v_mov_b32_e32 v44, v36
	s_waitcnt lgkmcnt(2)
	v_mov_b32_e32 v45, v38
	s_waitcnt lgkmcnt(1)
	v_mov_b32_e32 v46, v40
	s_waitcnt lgkmcnt(0)
	v_mov_b32_e32 v47, v42
	s_lshl_b32 s7, s7, 1
	s_and_b32 s6, s6, 0x60
	v_mov_b32_e32 v24, v6
	v_mov_b32_e32 v25, v28
	v_pk_mul_f32 v[26:27], v[18:19], v[26:27]
	v_pk_mul_f32 v[44:45], v[4:5], v[44:45]
	v_pk_mul_f32 v[46:47], v[2:3], v[46:47]
	s_or_b32 s6, s13, s6
	s_and_b32 s7, s7, 0xffffff00
	v_pk_mul_f32 v[24:25], v[0:1], v[24:25]
	v_bfe_u32 v28, v46, 16, 1
	v_bfe_u32 v34, v26, 16, 1
	v_bfe_u32 v36, v44, 16, 1
	s_or_b32 s6, s6, s7
	v_bfe_u32 v32, v27, 16, 1
	v_add3_u32 v34, v26, v34, s11
	v_add3_u32 v26, v46, v28, s11
	v_bfe_u32 v28, v25, 16, 1
	v_bfe_u32 v38, v45, 16, 1
	v_add3_u32 v36, v44, v36, s11
	v_bfe_u32 v6, v47, 16, 1
	v_add3_u32 v32, v27, v32, s11
	v_bfe_u32 v27, v24, 16, 1
	v_add3_u32 v38, v45, v38, s11
	v_add3_u32 v25, v25, v28, s11
	v_lshrrev_b32_e32 v28, 16, v36
	v_or_b32_e32 v44, s6, v13
	v_add3_u32 v6, v47, v6, s11
	v_add3_u32 v24, v24, v27, s11
	v_lshrrev_b32_e32 v27, 16, v38
	v_and_or_b32 v26, v26, s12, v28
	v_ashrrev_i32_e32 v45, 31, v44
	v_mov_b32_e32 v28, v7
	v_mov_b32_e32 v42, v41
	v_lshl_add_u64 v[30:31], s[4:5], 1, v[16:17]
	v_lshrrev_b32_e32 v24, 16, v24
	v_lshrrev_b32_e32 v25, 16, v25
	v_and_or_b32 v27, v6, s12, v27
	v_lshlrev_b64 v[44:45], 12, v[44:45]
	v_pk_mul_f32 v[6:7], v[0:1], v[28:29]
	v_pk_mul_f32 v[28:29], v[2:3], v[42:43]
	v_and_or_b32 v25, v32, s12, v25
	v_and_or_b32 v24, v34, s12, v24
	v_lshl_add_u64 v[44:45], v[30:31], 0, v[44:45]
	v_mov_b32_e32 v34, v33
	v_bfe_u32 v32, v29, 16, 1
	global_store_dwordx4 v[44:45], v[24:27], off
	v_bfe_u32 v33, v28, 16, 1
	v_add3_u32 v29, v29, v32, s11
	v_pk_mul_f32 v[24:25], v[18:19], v[34:35]
	v_bfe_u32 v32, v6, 16, 1
	v_mov_b32_e32 v38, v37
	v_bfe_u32 v35, v24, 16, 1
	v_add3_u32 v28, v28, v33, s11
	v_bfe_u32 v33, v7, 16, 1
	v_add3_u32 v6, v6, v32, s11
	v_pk_mul_f32 v[26:27], v[4:5], v[38:39]
	v_bfe_u32 v34, v25, 16, 1
	v_add3_u32 v24, v24, v35, s11
	v_add3_u32 v7, v7, v33, s11
	v_lshrrev_b32_e32 v6, 16, v6
	v_add3_u32 v25, v25, v34, s11
	v_bfe_u32 v34, v26, 16, 1
	v_bfe_u32 v35, v27, 16, 1
	v_lshrrev_b32_e32 v7, 16, v7
	v_and_or_b32 v24, v24, s12, v6
	v_or_b32_e32 v6, s6, v21
	v_add3_u32 v27, v27, v35, s11
	v_add3_u32 v26, v26, v34, s11
	v_and_or_b32 v25, v25, s12, v7
	v_ashrrev_i32_e32 v7, 31, v6
	v_lshrrev_b32_e32 v26, 16, v26
	v_lshrrev_b32_e32 v27, 16, v27
	v_lshlrev_b64 v[6:7], 12, v[6:7]
	v_and_or_b32 v27, v29, s12, v27
	v_and_or_b32 v26, v28, s12, v26
	v_lshl_add_u64 v[6:7], v[30:31], 0, v[6:7]
	ds_read2_b32 v[28:29], v20 offset0:16 offset1:24
	ds_read2_b32 v[32:33], v20 offset0:82 offset1:90
	global_store_dwordx4 v[6:7], v[24:27], off
	ds_read2_b32 v[6:7], v20 offset0:49 offset1:57
	ds_read2_b32 v[34:35], v20 offset0:115 offset1:123
	ds_read2_b32 v[36:37], v20 offset0:148 offset1:156
	ds_read2_b32 v[38:39], v20 offset0:214 offset1:222
	ds_read2_b32 v[40:41], v20 offset0:181 offset1:189
	ds_read2_b32 v[42:43], v20 offset0:247 offset1:255
	s_waitcnt lgkmcnt(7)
	v_mov_b32_e32 v24, v28
	s_waitcnt lgkmcnt(5)
	v_mov_b32_e32 v26, v6
	s_waitcnt lgkmcnt(4)
	v_mov_b32_e32 v27, v34
	v_mov_b32_e32 v25, v32
	v_pk_mul_f32 v[26:27], v[18:19], v[26:27]
	s_waitcnt lgkmcnt(3)
	v_mov_b32_e32 v44, v36
	s_waitcnt lgkmcnt(2)
	v_mov_b32_e32 v45, v38
	s_waitcnt lgkmcnt(1)
	v_mov_b32_e32 v46, v40
	s_waitcnt lgkmcnt(0)
	v_mov_b32_e32 v47, v42
	v_pk_mul_f32 v[24:25], v[0:1], v[24:25]
	v_pk_mul_f32 v[44:45], v[4:5], v[44:45]
	v_pk_mul_f32 v[46:47], v[2:3], v[46:47]
	v_bfe_u32 v32, v27, 16, 1
	v_bfe_u32 v28, v46, 16, 1
	v_bfe_u32 v34, v26, 16, 1
	v_add3_u32 v32, v27, v32, s11
	v_bfe_u32 v27, v24, 16, 1
	v_bfe_u32 v36, v44, 16, 1
	v_add3_u32 v34, v26, v34, s11
	v_add3_u32 v26, v46, v28, s11
	v_bfe_u32 v28, v25, 16, 1
	v_bfe_u32 v38, v45, 16, 1
	v_add3_u32 v36, v44, v36, s11
	v_add3_u32 v24, v24, v27, s11
	v_or_b32_e32 v44, s6, v22
	v_bfe_u32 v6, v47, 16, 1
	v_add3_u32 v38, v45, v38, s11
	v_add3_u32 v25, v25, v28, s11
	v_lshrrev_b32_e32 v24, 16, v24
	v_ashrrev_i32_e32 v45, 31, v44
	v_add3_u32 v6, v47, v6, s11
	v_lshrrev_b32_e32 v25, 16, v25
	v_lshrrev_b32_e32 v28, 16, v36
	v_lshrrev_b32_e32 v27, 16, v38
	v_and_or_b32 v24, v34, s12, v24
	v_lshlrev_b64 v[44:45], 12, v[44:45]
	v_mov_b32_e32 v34, v7
	v_and_or_b32 v27, v6, s12, v27
	v_and_or_b32 v26, v26, s12, v28
	v_and_or_b32 v25, v32, s12, v25
	v_lshl_add_u64 v[44:45], v[30:31], 0, v[44:45]
	v_pk_mul_f32 v[6:7], v[18:19], v[34:35]
	v_mov_b32_e32 v38, v37
	global_store_dwordx4 v[44:45], v[24:27], off
	v_pk_mul_f32 v[4:5], v[4:5], v[38:39]
	v_mov_b32_e32 v42, v41
	v_bfe_u32 v24, v7, 16, 1
	v_pk_mul_f32 v[2:3], v[2:3], v[42:43]
	v_bfe_u32 v25, v6, 16, 1
	v_add3_u32 v7, v7, v24, s11
	v_bfe_u32 v24, v4, 16, 1
	v_mov_b32_e32 v32, v29
	v_bfe_u32 v19, v2, 16, 1
	v_add3_u32 v6, v6, v25, s11
	v_bfe_u32 v25, v5, 16, 1
	v_add3_u32 v4, v4, v24, s11
	v_pk_mul_f32 v[0:1], v[0:1], v[32:33]
	v_bfe_u32 v18, v3, 16, 1
	v_add3_u32 v2, v2, v19, s11
	v_add3_u32 v5, v5, v25, s11
	v_lshrrev_b32_e32 v4, 16, v4
	v_add3_u32 v3, v3, v18, s11
	v_bfe_u32 v18, v0, 16, 1
	v_bfe_u32 v19, v1, 16, 1
	v_lshrrev_b32_e32 v5, 16, v5
	v_and_or_b32 v2, v2, s12, v4
	v_or_b32_e32 v4, s6, v23
	v_add3_u32 v1, v1, v19, s11
	v_add3_u32 v0, v0, v18, s11
	v_and_or_b32 v3, v3, s12, v5
	v_ashrrev_i32_e32 v5, 31, v4
	v_lshrrev_b32_e32 v0, 16, v0
	v_lshrrev_b32_e32 v1, 16, v1
	v_lshlrev_b64 v[4:5], 12, v[4:5]
	v_and_or_b32 v1, v7, s12, v1
	v_and_or_b32 v0, v6, s12, v0
	v_lshl_add_u64 v[4:5], v[30:31], 0, v[4:5]
	global_store_dwordx4 v[4:5], v[0:3], off
	s_waitcnt lgkmcnt(0)
	s_add_i32 s8, s8, s98
	s_cmp_lt_i32 s8, s99
	s_cbranch_scc0 .Lcv_p1a_exit

; #define LAS __attribute__((address_space(3)))
; __device__ __forceinline__ void conv_matrix(const float* W, int K, int ldn, int c0, int ncols, bf16_t* WT, int drow0, int mode, const float* gain, LAS unsigned char* lds) {
;     ...
;     for (int it = gw; it < nitems; it += ngw) {
;         const int kb = it / nblk, nb = it - kb * nblk, k0 = 64 * kb, n0 = c0 + 32 * nb;
;         int drow;
;         if (mode == 1) { const int up = n0 >= FF ? 1 : 0, j = n0 - up * FF; drow = (j >> 7) * 256 + up * 128 + (j & 127); } else drow = drow0 + 32 * nb;
; #pragma unroll 8
;         for (int i = 0; i < 32; ++i) { const int kk = 2 * i + (lane >> 5); scr[kk * 33 + (lane & 31)] = W[(size_t)(k0 + kk) * ldn + n0 + (lane & 31)]; }
;         asm volatile("s_waitcnt lgkmcnt(0)" ::: "memory");
;         const int c = lane & 7;
;         f32x4 g0 = {1.f, 1.f, 1.f, 1.f}, g1 = {1.f, 1.f, 1.f, 1.f};
;         if (gain) { g0 = *(const f32x4*)(gain + k0 + 8 * c); g1 = *(const f32x4*)(gain + k0 + 8 * c + 4); }
; #pragma unroll
;         for (int j = 0; j < 4; ++j) { const int n = (lane >> 3) + 8 * j; const LAS float* s = scr + (8 * c) * 33 + n;
.Lcv_p1a_exit:
	s_cmp_lg_u32 s72, 0x800
	s_cbranch_scc1 .LBB0_433
	s_cmp_lg_u32 s101, 0
	s_cbranch_scc1 .LBB0_433
	s_cmp_lt_u32 s97, 0x200
	s_cbranch_scc1 .LBB0_433
	s_mov_b32 s101, 1
	s_branch .Lcv_p1a_top
.LBB0_433:
	s_mov_b32 s101, 0
.Lcv_p1b_top:
	v_mov_b32_e32 v1, v204
	s_nop 0
	v_readfirstlane_b32 s0, v1
	s_ashr_i32 s0, s0, 6
	s_add_i32 s6, s0, s97
	s_mov_b32 s98, s72
	s_movk_i32 s99, 0x1600
	s_cmp_lg_u32 s72, 0x800
	s_cbranch_scc1 .Lcv_p1b_go
	s_cmp_eq_u32 s101, 0
	s_cbranch_scc0 .Lcv_p1b_second
	s_movk_i32 s99, 2048
	s_branch .Lcv_p1b_go
.Lcv_p1b_second:
	s_add_i32 s6, s6, 1536
	s_movk_i32 s98, 0x600
.Lcv_p1b_go:
	s_cmp_ge_i32 s6, s99
	s_cbranch_scc1 .Lcv_p1b_exit
	s_lshl_b32 s0, s0, 14
	v_lshlrev_b32_e32 v2, 2, v1
	v_readlane_b32 s36, v249, 8
	s_add_i32 s0, s0, 0
	v_and_b32_e32 v6, 0x7c, v2
	v_mov_b32_e32 v7, 0
	v_readlane_b32 s37, v249, 9
	v_and_b32_e32 v5, 7, v1
	s_waitcnt vmcnt(0)
	v_bfe_u32 v11, v1, 3, 3
	v_readlane_b32 s4, v249, 24
	v_bfe_u32 v0, v1, 5, 1
	v_lshl_add_u64 v[2:3], s[36:37], 0, v[6:7]
	v_add_u32_e32 v4, s0, v6
	v_mul_u32_u24_e32 v1, 0x420, v5
	v_lshlrev_b32_e32 v6, 4, v5
	v_readlane_b32 s5, v249, 25
	v_lshlrev_b32_e32 v5, 2, v11
	v_add3_u32 v12, s0, v1, v5
	v_lshl_add_u64 v[6:7], s[4:5], 0, v[6:7]
	v_or_b32_e32 v13, 8, v11
	v_or_b32_e32 v14, 16, v11
	v_or_b32_e32 v15, 24, v11
	v_mov_b32_e32 v1, v0
	s_movk_i32 s7, 0x84
	s_movk_i32 s8, 0x7fff
	s_mov_b32 s9, 0xffff0000
	s_movk_i32 s10, 0x2c00
	v_readlane_b32 s38, v249, 10
	v_readlane_b32 s39, v249, 11
	v_readlane_b32 s40, v249, 12
	v_readlane_b32 s41, v249, 13
	v_readlane_b32 s42, v249, 14
	v_readlane_b32 s43, v249, 15
	v_readlane_b32 s44, v249, 16
	v_readlane_b32 s45, v249, 17
	v_readlane_b32 s46, v249, 18
	v_readlane_b32 s47, v249, 19
	v_readlane_b32 s48, v249, 20
	v_readlane_b32 s49, v249, 21
	v_readlane_b32 s50, v249, 22
	v_readlane_b32 s51, v249, 23

; __device__ __forceinline__ void conv_matrix(const float* W, int K, int ldn, int c0, int ncols, bf16_t* WT, int drow0, int mode, const float* gain, LAS unsigned char* lds) {
;     ...
; #pragma unroll 8
;         for (int i = 0; i < 32; ++i) { const int kk = 2 * i + (lane >> 5); scr[kk * 33 + (lane & 31)] = W[(size_t)(k0 + kk) * ldn + n0 + (lane & 31)]; }
.LBB0_436:
	s_lshl_b32 s12, s11, 1
	s_lshl_b32 s13, s5, 1
	v_or_b32_e32 v18, s13, v10
	s_add_i32 s20, s12, 4
	s_add_i32 s21, s13, 4
	s_add_i32 s22, s12, 8
	s_add_i32 s23, s13, 8
	s_add_i32 s24, s12, 12
	s_add_i32 s25, s13, 12
	s_add_i32 s26, s12, 16
	s_add_i32 s27, s13, 16
	s_add_i32 s28, s12, 20
	s_add_i32 s29, s13, 20
	s_add_i32 s30, s12, 24
	s_add_i32 s31, s13, 24
	s_add_i32 s33, s12, 28
	s_add_i32 s34, s13, 28
	v_or_b32_e32 v16, s12, v5
	v_ashrrev_i32_e32 v19, 31, v18
	v_or_b32_e32 v20, s20, v5
	v_or_b32_e32 v22, s21, v10
	v_or_b32_e32 v24, s22, v5
	v_or_b32_e32 v26, s23, v10
	v_or_b32_e32 v28, s24, v5
	v_or_b32_e32 v30, s25, v10
	v_or_b32_e32 v32, s26, v5
	v_or_b32_e32 v34, s27, v10
	v_or_b32_e32 v36, s28, v5
	v_or_b32_e32 v38, s29, v10
	v_or_b32_e32 v40, s30, v5
	v_or_b32_e32 v42, s31, v10
	v_or_b32_e32 v44, s33, v5
	v_or_b32_e32 v46, s34, v10
	v_ashrrev_i32_e32 v17, 31, v16
	v_lshlrev_b64 v[18:19], 13, v[18:19]
	v_ashrrev_i32_e32 v23, 31, v22
	v_ashrrev_i32_e32 v21, 31, v20
	v_ashrrev_i32_e32 v27, 31, v26
	v_ashrrev_i32_e32 v25, 31, v24
	v_ashrrev_i32_e32 v31, 31, v30
	v_ashrrev_i32_e32 v29, 31, v28
	v_ashrrev_i32_e32 v35, 31, v34
	v_ashrrev_i32_e32 v33, 31, v32
	v_ashrrev_i32_e32 v39, 31, v38
	v_ashrrev_i32_e32 v37, 31, v36
	v_ashrrev_i32_e32 v43, 31, v42
	v_ashrrev_i32_e32 v41, 31, v40
	v_ashrrev_i32_e32 v47, 31, v46
	v_ashrrev_i32_e32 v45, 31, v44
	v_lshlrev_b64 v[16:17], 13, v[16:17]
	v_lshl_add_u64 v[18:19], v[8:9], 0, v[18:19]
	v_lshlrev_b64 v[20:21], 13, v[20:21]
	v_lshlrev_b64 v[22:23], 13, v[22:23]
	v_lshlrev_b64 v[24:25], 13, v[24:25]
	v_lshlrev_b64 v[26:27], 13, v[26:27]
	v_lshlrev_b64 v[28:29], 13, v[28:29]
	v_lshlrev_b64 v[30:31], 13, v[30:31]
	v_lshlrev_b64 v[32:33], 13, v[32:33]
	v_lshlrev_b64 v[34:35], 13, v[34:35]
	v_lshlrev_b64 v[36:37], 13, v[36:37]
	v_lshlrev_b64 v[38:39], 13, v[38:39]
	v_lshlrev_b64 v[40:41], 13, v[40:41]
	v_lshlrev_b64 v[42:43], 13, v[42:43]
	v_lshlrev_b64 v[44:45], 13, v[44:45]
	v_lshlrev_b64 v[46:47], 13, v[46:47]
	v_lshl_add_u64 v[16:17], v[8:9], 0, v[16:17]
	v_lshl_add_u64 v[22:23], v[8:9], 0, v[22:23]
	v_lshl_add_u64 v[20:21], v[8:9], 0, v[20:21]
	v_lshl_add_u64 v[26:27], v[8:9], 0, v[26:27]
	v_lshl_add_u64 v[24:25], v[8:9], 0, v[24:25]
	v_lshl_add_u64 v[30:31], v[8:9], 0, v[30:31]
	v_lshl_add_u64 v[28:29], v[8:9], 0, v[28:29]
	v_lshl_add_u64 v[34:35], v[8:9], 0, v[34:35]
	v_lshl_add_u64 v[32:33], v[8:9], 0, v[32:33]
	v_lshl_add_u64 v[38:39], v[8:9], 0, v[38:39]
	v_lshl_add_u64 v[36:37], v[8:9], 0, v[36:37]
	v_lshl_add_u64 v[42:43], v[8:9], 0, v[42:43]
	v_lshl_add_u64 v[40:41], v[8:9], 0, v[40:41]
	v_lshl_add_u64 v[46:47], v[8:9], 0, v[46:47]
	v_lshl_add_u64 v[44:45], v[8:9], 0, v[44:45]
	global_load_dword v48, v[18:19], off
	global_load_dword v49, v[16:17], off
	global_load_dword v50, v[22:23], off
	global_load_dword v51, v[20:21], off
	global_load_dword v52, v[26:27], off
	global_load_dword v53, v[24:25], off
	global_load_dword v54, v[30:31], off
	global_load_dword v55, v[28:29], off
	global_load_dword v56, v[34:35], off
	global_load_dword v57, v[32:33], off
	global_load_dword v58, v[38:39], off
	global_load_dword v59, v[36:37], off
	global_load_dword v60, v[42:43], off
	global_load_dword v61, v[40:41], off
	global_load_dword v62, v[46:47], off
	global_load_dword v63, v[44:45], off
	v_or_b32_e32 v18, s12, v1
	v_or_b32_e32 v16, s13, v0
	s_add_i32 s5, s5, 16
	s_add_i32 s11, s11, 16
	s_add_i32 s1, s1, -16
	v_mad_u64_u32 v[16:17], s[12:13], v16, s7, v[4:5]
	v_mad_u64_u32 v[18:19], s[12:13], v18, s7, v[4:5]
	v_or_b32_e32 v17, s20, v1
	v_or_b32_e32 v19, s21, v0
	v_or_b32_e32 v26, s22, v1
	v_or_b32_e32 v24, s23, v0
	v_or_b32_e32 v30, s24, v1
	v_or_b32_e32 v28, s25, v0
	v_or_b32_e32 v34, s26, v1
	v_or_b32_e32 v32, s27, v0
	v_or_b32_e32 v38, s28, v1
	v_or_b32_e32 v36, s29, v0
	v_or_b32_e32 v42, s30, v1
	v_or_b32_e32 v40, s31, v0
	v_or_b32_e32 v46, s33, v1
	v_or_b32_e32 v44, s34, v0
	s_cmp_lg_u32 s1, 0
	v_mad_u64_u32 v[20:21], s[12:13], v19, s7, v[4:5]
	v_mad_u64_u32 v[22:23], s[12:13], v17, s7, v[4:5]
	v_mad_u64_u32 v[24:25], s[12:13], v24, s7, v[4:5]
	v_mad_u64_u32 v[26:27], s[12:13], v26, s7, v[4:5]
	v_mad_u64_u32 v[28:29], s[12:13], v28, s7, v[4:5]
	v_mad_u64_u32 v[30:31], s[12:13], v30, s7, v[4:5]
	v_mad_u64_u32 v[32:33], s[12:13], v32, s7, v[4:5]
	v_mad_u64_u32 v[34:35], s[12:13], v34, s7, v[4:5]
	v_mad_u64_u32 v[36:37], s[12:13], v36, s7, v[4:5]
	v_mad_u64_u32 v[38:39], s[12:13], v38, s7, v[4:5]
	v_mad_u64_u32 v[40:41], s[12:13], v40, s7, v[4:5]
	v_mad_u64_u32 v[42:43], s[12:13], v42, s7, v[4:5]
	v_mad_u64_u32 v[44:45], s[12:13], v44, s7, v[4:5]
	v_mad_u64_u32 v[46:47], s[12:13], v46, s7, v[4:5]
	s_waitcnt vmcnt(15)
	ds_write_b32 v16, v48
	s_waitcnt vmcnt(14)
	ds_write_b32 v18, v49
	s_waitcnt vmcnt(13)
	ds_write_b32 v20, v50
	s_waitcnt vmcnt(12)
	ds_write_b32 v22, v51
	s_waitcnt vmcnt(11)
	ds_write_b32 v24, v52
	s_waitcnt vmcnt(10)
	ds_write_b32 v26, v53
	s_waitcnt vmcnt(9)
	ds_write_b32 v28, v54
	s_waitcnt vmcnt(8)
	ds_write_b32 v30, v55
	s_waitcnt vmcnt(7)
	ds_write_b32 v32, v56
	s_waitcnt vmcnt(6)
	ds_write_b32 v34, v57
	s_waitcnt vmcnt(5)
	ds_write_b32 v36, v58
	s_waitcnt vmcnt(4)
	ds_write_b32 v38, v59
	s_waitcnt vmcnt(3)
	ds_write_b32 v40, v60
	s_waitcnt vmcnt(2)
	ds_write_b32 v42, v61
	s_waitcnt vmcnt(1)
	ds_write_b32 v44, v62
	s_waitcnt vmcnt(0)
	ds_write_b32 v46, v63
	s_cbranch_scc1 .LBB0_436
; #define LAS __attribute__((address_space(3)))
; __device__ __forceinline__ unsigned pk2(float lo, float hi) { return f2bf(lo) | (f2bf(hi) << 16); }
; __device__ __forceinline__ void conv_matrix(const float* W, int K, int ldn, int c0, int ncols, bf16_t* WT, int drow0, int mode, const float* gain, LAS unsigned char* lds) {
;     ...
;         for (int j = 0; j < 4; ++j) { const int n = (lane >> 3) + 8 * j; const LAS float* s = scr + (8 * c) * 33 + n;
;             u32x4 o; o.x = pk2(s[0 * 33] * g0.x, s[1 * 33] * g0.y); o.y = pk2(s[2 * 33] * g0.z, s[3 * 33] * g0.w); o.z = pk2(s[4 * 33] * g1.x, s[5 * 33] * g1.y); o.w = pk2(s[6 * 33] * g1.z, s[7 * 33] * g1.w);
;             *(u32x4*)(WT + (size_t)(drow + n) * K + k0 + 8 * c) = o; }
;         asm volatile("s_waitcnt lgkmcnt(0)" ::: "memory");
;     }
	s_waitcnt lgkmcnt(0)
	ds_read2_b32 v[8:9], v12 offset1:8
	ds_read2_b32 v[22:23], v12 offset0:33 offset1:41
	ds_read2_b32 v[24:25], v12 offset0:66 offset1:74
	ds_read2_b32 v[26:27], v12 offset0:99 offset1:107
	ds_read2_b32 v[28:29], v12 offset0:132 offset1:140
	ds_read2_b32 v[30:31], v12 offset0:165 offset1:173
	s_waitcnt lgkmcnt(5)
	v_bfe_u32 v5, v8, 16, 1
	v_add3_u32 v5, v8, v5, s8
	s_waitcnt lgkmcnt(4)
	v_bfe_u32 v8, v22, 16, 1
	v_lshrrev_b32_e32 v5, 16, v5
	v_add3_u32 v8, v22, v8, s8
	v_and_or_b32 v16, v8, s9, v5
	s_waitcnt lgkmcnt(3)
	v_bfe_u32 v5, v24, 16, 1
	v_add3_u32 v5, v24, v5, s8
	s_waitcnt lgkmcnt(2)
	v_bfe_u32 v8, v26, 16, 1
	ds_read2_b32 v[32:33], v12 offset0:198 offset1:206
	v_lshrrev_b32_e32 v5, 16, v5
	v_add3_u32 v8, v26, v8, s8
	ds_read2_b32 v[34:35], v12 offset0:231 offset1:239
	v_and_or_b32 v17, v8, s9, v5
	s_waitcnt lgkmcnt(3)
	v_bfe_u32 v5, v28, 16, 1
	v_add3_u32 v5, v28, v5, s8
	s_waitcnt lgkmcnt(2)
	v_bfe_u32 v8, v30, 16, 1
	v_lshrrev_b32_e32 v5, 16, v5
	v_add3_u32 v8, v30, v8, s8
	v_and_or_b32 v18, v8, s9, v5
	s_waitcnt lgkmcnt(1)
	v_bfe_u32 v5, v32, 16, 1
	v_add3_u32 v5, v32, v5, s8
	s_waitcnt lgkmcnt(0)
	v_bfe_u32 v8, v34, 16, 1
	s_ashr_i32 s5, s4, 31
	v_lshrrev_b32_e32 v5, 16, v5
	v_add3_u32 v8, v34, v8, s8
	v_lshl_add_u64 v[20:21], s[4:5], 1, v[6:7]
	v_and_or_b32 v19, v8, s9, v5
	v_or_b32_e32 v5, s0, v11
	v_mad_i64_i32 v[36:37], s[4:5], v5, s10, v[20:21]
	v_bfe_u32 v5, v9, 16, 1
	v_add3_u32 v5, v9, v5, s8
	v_bfe_u32 v8, v23, 16, 1
	v_lshrrev_b32_e32 v5, 16, v5
	v_add3_u32 v8, v23, v8, s8
	global_store_dwordx4 v[36:37], v[16:19], off
	s_add_i32 s6, s6, s98
	s_cmp_lt_i32 s6, s99
	v_and_or_b32 v16, v8, s9, v5
	v_bfe_u32 v5, v25, 16, 1
	v_add3_u32 v5, v25, v5, s8
	v_bfe_u32 v8, v27, 16, 1
	v_lshrrev_b32_e32 v5, 16, v5
	v_add3_u32 v8, v27, v8, s8
	v_and_or_b32 v17, v8, s9, v5
	v_bfe_u32 v5, v29, 16, 1
	v_add3_u32 v5, v29, v5, s8
	v_bfe_u32 v8, v31, 16, 1
	v_lshrrev_b32_e32 v5, 16, v5
	v_add3_u32 v8, v31, v8, s8
	v_and_or_b32 v18, v8, s9, v5
	v_bfe_u32 v5, v33, 16, 1
	v_add3_u32 v5, v33, v5, s8
	v_bfe_u32 v8, v35, 16, 1
	v_lshrrev_b32_e32 v5, 16, v5
	v_add3_u32 v8, v35, v8, s8
	v_and_or_b32 v19, v8, s9, v5
	v_or_b32_e32 v5, s0, v13
	ds_read2_b32 v[8:9], v12 offset0:16 offset1:24
	v_mad_i64_i32 v[22:23], s[4:5], v5, s10, v[20:21]
	global_store_dwordx4 v[22:23], v[16:19], off
	ds_read2_b32 v[22:23], v12 offset0:49 offset1:57
	ds_read2_b32 v[24:25], v12 offset0:82 offset1:90
	ds_read2_b32 v[26:27], v12 offset0:115 offset1:123
	s_waitcnt lgkmcnt(3)
	v_bfe_u32 v5, v8, 16, 1
	v_add3_u32 v5, v8, v5, s8
	s_waitcnt lgkmcnt(2)
	v_bfe_u32 v8, v22, 16, 1
	ds_read2_b32 v[28:29], v12 offset0:148 offset1:156
	v_lshrrev_b32_e32 v5, 16, v5
	v_add3_u32 v8, v22, v8, s8
	ds_read2_b32 v[30:31], v12 offset0:181 offset1:189
	v_and_or_b32 v16, v8, s9, v5
	s_waitcnt lgkmcnt(3)
	v_bfe_u32 v5, v24, 16, 1
	v_add3_u32 v5, v24, v5, s8
	s_waitcnt lgkmcnt(2)
	v_bfe_u32 v8, v26, 16, 1
	ds_read2_b32 v[32:33], v12 offset0:214 offset1:222
	v_lshrrev_b32_e32 v5, 16, v5
	v_add3_u32 v8, v26, v8, s8
	ds_read2_b32 v[34:35], v12 offset0:247 offset1:255
	v_and_or_b32 v17, v8, s9, v5
	s_waitcnt lgkmcnt(3)
	v_bfe_u32 v5, v28, 16, 1
	v_add3_u32 v5, v28, v5, s8
	s_waitcnt lgkmcnt(2)
	v_bfe_u32 v8, v30, 16, 1
	v_lshrrev_b32_e32 v5, 16, v5
	v_add3_u32 v8, v30, v8, s8
	v_and_or_b32 v18, v8, s9, v5
	s_waitcnt lgkmcnt(1)
	v_bfe_u32 v5, v32, 16, 1
	v_add3_u32 v5, v32, v5, s8
	s_waitcnt lgkmcnt(0)
	v_bfe_u32 v8, v34, 16, 1
	v_lshrrev_b32_e32 v5, 16, v5
	v_add3_u32 v8, v34, v8, s8
	v_and_or_b32 v19, v8, s9, v5
	v_or_b32_e32 v5, s0, v14
	v_mad_i64_i32 v[36:37], s[4:5], v5, s10, v[20:21]
	v_bfe_u32 v5, v9, 16, 1
	v_add3_u32 v5, v9, v5, s8
	v_bfe_u32 v8, v23, 16, 1
	v_lshrrev_b32_e32 v5, 16, v5
	v_add3_u32 v8, v23, v8, s8
	global_store_dwordx4 v[36:37], v[16:19], off
	s_nop 1
	v_and_or_b32 v16, v8, s9, v5
	v_bfe_u32 v5, v25, 16, 1
	v_add3_u32 v5, v25, v5, s8
	v_bfe_u32 v8, v27, 16, 1
	v_lshrrev_b32_e32 v5, 16, v5
	v_add3_u32 v8, v27, v8, s8
	v_and_or_b32 v17, v8, s9, v5
	v_bfe_u32 v5, v29, 16, 1
	v_add3_u32 v5, v29, v5, s8
	v_bfe_u32 v8, v31, 16, 1
	v_lshrrev_b32_e32 v5, 16, v5
	v_add3_u32 v8, v31, v8, s8
	v_and_or_b32 v18, v8, s9, v5
	v_bfe_u32 v5, v33, 16, 1
	v_add3_u32 v5, v33, v5, s8
	v_bfe_u32 v8, v35, 16, 1
	v_lshrrev_b32_e32 v5, 16, v5
	v_add3_u32 v8, v35, v8, s8
	v_and_or_b32 v19, v8, s9, v5
	v_or_b32_e32 v5, s0, v15
	v_mad_i64_i32 v[8:9], s[0:1], v5, s10, v[20:21]
	global_store_dwordx4 v[8:9], v[16:19], off
	s_waitcnt lgkmcnt(0)
	s_cbranch_scc1 .LBB0_435

; #define LAS __attribute__((address_space(3)))
; __device__ __forceinline__ int opaque_tid() { int t = threadIdx.x; asm volatile("" : "+v"(t)); return t; }
; __device__ __forceinline__ void conv_matrix(const float* W, int K, int ldn, int c0, int ncols, bf16_t* WT, int drow0, int mode, const float* gain, LAS unsigned char* lds) {
;     const int tid = opaque_tid(), lane = tid & 63, wave = __builtin_amdgcn_readfirstlane(tid >> 6), gw = blockIdx.x * NWAVES + wave, ngw = gridDim.x * NWAVES;
;     LAS float* scr = (LAS float*)(lds + wave * 16384);
;     const int nblk = ncols / 32, nitems = (K / 64) * nblk;
;     for (int it = gw; it < nitems; it += ngw) {
;         const int kb = it / nblk, nb = it - kb * nblk, k0 = 64 * kb, n0 = c0 + 32 * nb;
;         int drow;
;         if (mode == 1) { const int up = n0 >= FF ? 1 : 0, j = n0 - up * FF; drow = (j >> 7) * 256 + up * 128 + (j & 127); } else drow = drow0 + 32 * nb;
; #pragma unroll 8
;         for (int i = 0; i < 32; ++i) { const int kk = 2 * i + (lane >> 5); scr[kk * 33 + (lane & 31)] = W[(size_t)(k0 + kk) * ldn + n0 + (lane & 31)]; }
;         asm volatile("s_waitcnt lgkmcnt(0)" ::: "memory");
;         const int c = lane & 7;
;         f32x4 g0 = {1.f, 1.f, 1.f, 1.f}, g1 = {1.f, 1.f, 1.f, 1.f};
;         if (gain) { g0 = *(const f32x4*)(gain + k0 + 8 * c); g1 = *(const f32x4*)(gain + k0 + 8 * c + 4); }
.Lcv_p2a_top:
	v_mov_b32_e32 v0, v204
	s_nop 0
	v_readfirstlane_b32 s0, v0
	s_ashr_i32 s0, s0, 6
	s_add_i32 s4, s0, s97
	s_mov_b32 s98, s72
	s_movk_i32 s99, 0x2c00
	s_cmp_lg_u32 s72, 0x800
	s_cbranch_scc1 .Lcv_p2a_go
	s_cmp_eq_u32 s101, 0
	s_cbranch_scc0 .Lcv_p2a_second
	s_movk_i32 s99, 4096
	s_branch .Lcv_p2a_go
.Lcv_p2a_second:
	s_add_i32 s4, s4, 3584
	s_movk_i32 s98, 0x600
.Lcv_p2a_go:
	s_cmp_lt_i32 s4, s99
	s_cbranch_scc0 .Lcv_p2a_exit
	s_lshl_b32 s0, s0, 14
	v_lshlrev_b32_e32 v1, 2, v0
	s_add_i32 s2, s0, 0
	v_and_b32_e32 v2, 0x7c, v1
	v_mov_b32_e32 v3, 0
	v_and_b32_e32 v1, 7, v0
	v_lshl_add_u64 v[4:5], s[70:71], 0, v[2:3]
	s_mov_b64 s[0:1], 0x5800000
	v_add_u32_e32 v12, s2, v2
	v_lshlrev_b32_e32 v2, 5, v1
	v_bfe_u32 v13, v0, 3, 3
	v_bfe_u32 v8, v0, 5, 1
	v_lshl_add_u64 v[10:11], v[4:5], 0, s[0:1]
	v_lshl_add_u64 v[4:5], s[68:69], 0, v[2:3]
	s_mov_b64 s[0:1], 0x2000
	v_mul_u32_u24_e32 v0, 0x420, v1
	v_lshlrev_b32_e32 v2, 4, v1
	v_lshlrev_b32_e32 v1, 2, v13
	v_lshl_add_u64 v[14:15], v[4:5], 0, s[0:1]
	v_lshl_add_u64 v[16:17], s[78:79], 0, v[2:3]
	v_add3_u32 v20, s2, v0, v1
	v_or_b32_e32 v21, 8, v13
	v_or_b32_e32 v22, 16, v13
	v_or_b32_e32 v23, 24, v13
	v_mov_b32_e32 v9, v8
	s_mov_b32 s5, 0xb000
	s_movk_i32 s6, 0x84
	s_movk_i32 s7, 0x7fff
	s_mov_b32 s8, 0xffff0000

; __device__ __forceinline__ void conv_matrix(const float* W, int K, int ldn, int c0, int ncols, bf16_t* WT, int drow0, int mode, const float* gain, LAS unsigned char* lds) {
;     ...
; #pragma unroll 8
;         for (int i = 0; i < 32; ++i) { const int kk = 2 * i + (lane >> 5); scr[kk * 33 + (lane & 31)] = W[(size_t)(k0 + kk) * ldn + n0 + (lane & 31)]; }
.LBB0_1344:
	s_lshl_b32 s11, s10, 1
	s_lshl_b32 s16, s9, 1
	v_or_b32_e32 v4, s16, v2
	s_add_i32 s17, s11, 4
	s_add_i32 s18, s16, 4
	s_add_i32 s19, s11, 8
	s_add_i32 s20, s16, 8
	s_add_i32 s21, s11, 12
	s_add_i32 s22, s16, 12
	s_add_i32 s23, s11, 16
	s_add_i32 s24, s16, 16
	s_add_i32 s25, s11, 20
	s_add_i32 s26, s16, 20
	s_add_i32 s27, s11, 24
	s_add_i32 s28, s16, 24
	s_add_i32 s29, s11, 28
	s_add_i32 s30, s16, 28
	v_or_b32_e32 v6, s11, v3
	v_mad_i64_i32 v[4:5], s[14:15], v4, s5, v[0:1]
	v_or_b32_e32 v24, s17, v3
	v_or_b32_e32 v18, s18, v2
	v_or_b32_e32 v28, s19, v3
	v_or_b32_e32 v26, s20, v2
	v_or_b32_e32 v32, s21, v3
	v_or_b32_e32 v30, s22, v2
	v_or_b32_e32 v36, s23, v3
	v_or_b32_e32 v34, s24, v2
	v_or_b32_e32 v40, s25, v3
	v_or_b32_e32 v38, s26, v2
	v_or_b32_e32 v44, s27, v3
	v_or_b32_e32 v42, s28, v2
	v_or_b32_e32 v48, s29, v3
	v_or_b32_e32 v46, s30, v2
	v_mad_i64_i32 v[6:7], s[14:15], v6, s5, v[0:1]
	v_mad_i64_i32 v[18:19], s[14:15], v18, s5, v[0:1]
	v_mad_i64_i32 v[24:25], s[14:15], v24, s5, v[0:1]
	v_mad_i64_i32 v[26:27], s[14:15], v26, s5, v[0:1]
	v_mad_i64_i32 v[28:29], s[14:15], v28, s5, v[0:1]
	v_mad_i64_i32 v[30:31], s[14:15], v30, s5, v[0:1]
	v_mad_i64_i32 v[32:33], s[14:15], v32, s5, v[0:1]
	v_mad_i64_i32 v[34:35], s[14:15], v34, s5, v[0:1]
	v_mad_i64_i32 v[36:37], s[14:15], v36, s5, v[0:1]
	v_mad_i64_i32 v[38:39], s[14:15], v38, s5, v[0:1]
	v_mad_i64_i32 v[40:41], s[14:15], v40, s5, v[0:1]
	v_mad_i64_i32 v[42:43], s[14:15], v42, s5, v[0:1]
	v_mad_i64_i32 v[44:45], s[14:15], v44, s5, v[0:1]
	v_mad_i64_i32 v[46:47], s[14:15], v46, s5, v[0:1]
	v_mad_i64_i32 v[48:49], s[14:15], v48, s5, v[0:1]
	global_load_dword v50, v[4:5], off
	global_load_dword v51, v[6:7], off
	global_load_dword v52, v[18:19], off
	global_load_dword v53, v[24:25], off
	global_load_dword v54, v[26:27], off
	global_load_dword v55, v[28:29], off
	global_load_dword v56, v[30:31], off
	global_load_dword v57, v[32:33], off
	global_load_dword v58, v[34:35], off
	global_load_dword v59, v[36:37], off
	global_load_dword v60, v[38:39], off
	global_load_dword v61, v[40:41], off
	global_load_dword v62, v[42:43], off
	global_load_dword v63, v[44:45], off
	global_load_dword v64, v[46:47], off
	global_load_dword v65, v[48:49], off
	v_or_b32_e32 v6, s11, v9
	v_or_b32_e32 v4, s16, v8
	s_add_i32 s9, s9, 16
	s_add_i32 s10, s10, 16
	s_add_i32 s3, s3, -16
	v_mad_u64_u32 v[4:5], s[14:15], v4, s6, v[12:13]
	v_mad_u64_u32 v[6:7], s[14:15], v6, s6, v[12:13]
	v_or_b32_e32 v5, s17, v9
	v_or_b32_e32 v7, s18, v8
	v_or_b32_e32 v28, s19, v9
	v_or_b32_e32 v26, s20, v8
	v_or_b32_e32 v32, s21, v9
	v_or_b32_e32 v30, s22, v8
	v_or_b32_e32 v36, s23, v9
	v_or_b32_e32 v34, s24, v8
	v_or_b32_e32 v40, s25, v9
	v_or_b32_e32 v38, s26, v8
	v_or_b32_e32 v44, s27, v9
	v_or_b32_e32 v42, s28, v8
	v_or_b32_e32 v48, s29, v9
	v_or_b32_e32 v46, s30, v8
	s_cmp_lg_u32 s3, 0
	v_mad_u64_u32 v[18:19], s[14:15], v7, s6, v[12:13]
	v_mad_u64_u32 v[24:25], s[14:15], v5, s6, v[12:13]
	v_mad_u64_u32 v[26:27], s[14:15], v26, s6, v[12:13]
	v_mad_u64_u32 v[28:29], s[14:15], v28, s6, v[12:13]
	v_mad_u64_u32 v[30:31], s[14:15], v30, s6, v[12:13]
	v_mad_u64_u32 v[32:33], s[14:15], v32, s6, v[12:13]
	v_mad_u64_u32 v[34:35], s[14:15], v34, s6, v[12:13]
	v_mad_u64_u32 v[36:37], s[14:15], v36, s6, v[12:13]
	v_mad_u64_u32 v[38:39], s[14:15], v38, s6, v[12:13]
	v_mad_u64_u32 v[40:41], s[14:15], v40, s6, v[12:13]
	v_mad_u64_u32 v[42:43], s[14:15], v42, s6, v[12:13]
	v_mad_u64_u32 v[44:45], s[14:15], v44, s6, v[12:13]
	v_mad_u64_u32 v[46:47], s[14:15], v46, s6, v[12:13]
	v_mad_u64_u32 v[48:49], s[14:15], v48, s6, v[12:13]
	s_waitcnt vmcnt(15)
	ds_write_b32 v4, v50
	s_waitcnt vmcnt(14)
	ds_write_b32 v6, v51
	s_waitcnt vmcnt(13)
	ds_write_b32 v18, v52
	s_waitcnt vmcnt(12)
	ds_write_b32 v24, v53
	s_waitcnt vmcnt(11)
	ds_write_b32 v26, v54
	s_waitcnt vmcnt(10)
	ds_write_b32 v28, v55
	s_waitcnt vmcnt(9)
	ds_write_b32 v30, v56
	s_waitcnt vmcnt(8)
	ds_write_b32 v32, v57
	s_waitcnt vmcnt(7)
	ds_write_b32 v34, v58
	s_waitcnt vmcnt(6)
	ds_write_b32 v36, v59
	s_waitcnt vmcnt(5)
	ds_write_b32 v38, v60
	s_waitcnt vmcnt(4)
	ds_write_b32 v40, v61
	s_waitcnt vmcnt(3)
	ds_write_b32 v42, v62
	s_waitcnt vmcnt(2)
	ds_write_b32 v44, v63
	s_waitcnt vmcnt(1)
	ds_write_b32 v46, v64
	s_waitcnt vmcnt(0)
	ds_write_b32 v48, v65
	s_cbranch_scc1 .LBB0_1344
; #define LAS __attribute__((address_space(3)))
; __device__ __forceinline__ unsigned pk2(float lo, float hi) { return f2bf(lo) | (f2bf(hi) << 16); }
; __device__ __forceinline__ void conv_matrix(const float* W, int K, int ldn, int c0, int ncols, bf16_t* WT, int drow0, int mode, const float* gain, LAS unsigned char* lds) {
;     ...
;         if (mode == 1) { const int up = n0 >= FF ? 1 : 0, j = n0 - up * FF; drow = (j >> 7) * 256 + up * 128 + (j & 127); } else drow = drow0 + 32 * nb;
;     ...
;         const int c = lane & 7;
;         f32x4 g0 = {1.f, 1.f, 1.f, 1.f}, g1 = {1.f, 1.f, 1.f, 1.f};
;         if (gain) { g0 = *(const f32x4*)(gain + k0 + 8 * c); g1 = *(const f32x4*)(gain + k0 + 8 * c + 4); }
; #pragma unroll
;         for (int j = 0; j < 4; ++j) { const int n = (lane >> 3) + 8 * j; const LAS float* s = scr + (8 * c) * 33 + n;
;             u32x4 o; o.x = pk2(s[0 * 33] * g0.x, s[1 * 33] * g0.y); o.y = pk2(s[2 * 33] * g0.z, s[3 * 33] * g0.w); o.z = pk2(s[4 * 33] * g1.x, s[5 * 33] * g1.y); o.w = pk2(s[6 * 33] * g1.z, s[7 * 33] * g1.w);
;             *(u32x4*)(WT + (size_t)(drow + n) * K + k0 + 8 * c) = o; }
;         asm volatile("s_waitcnt lgkmcnt(0)" ::: "memory");
;     }
	s_cmpk_gt_i32 s1, 0xaf
	s_cselect_b32 s3, 0xffffea00, 0
	s_cselect_b32 s9, 0x80, 0
	s_ashr_i32 s1, s0, 31
	s_waitcnt lgkmcnt(0)
	v_lshl_add_u64 v[0:1], s[0:1], 2, v[14:15]
	global_load_dwordx4 v[4:7], v[0:1], off
	s_nop 0
	global_load_dwordx4 v[0:3], v[0:1], off offset:16
	s_add_i32 s3, s3, s2
	s_and_b32 s10, s2, 0x60
	ds_read2_b32 v[24:25], v20 offset0:33 offset1:41
	ds_read2_b32 v[26:27], v20 offset0:66 offset1:74
	ds_read2_b32 v[28:29], v20 offset0:99 offset1:107
	ds_read2_b32 v[30:31], v20 offset1:8
	ds_read2_b32 v[32:33], v20 offset0:132 offset1:140
	ds_read2_b32 v[34:35], v20 offset0:165 offset1:173
	ds_read2_b32 v[36:37], v20 offset0:198 offset1:206
	ds_read2_b32 v[38:39], v20 offset0:231 offset1:239
	v_lshl_add_u64 v[18:19], s[0:1], 1, v[16:17]
	s_lshl_b32 s0, s3, 1
	s_or_b32 s2, s9, s10
	s_and_b32 s0, s0, 0xffffff00
	s_or_b32 s0, s2, s0
	s_waitcnt lgkmcnt(7)
	v_mov_b32_e32 v42, v24
	v_or_b32_e32 v24, s0, v13
	s_waitcnt lgkmcnt(4)
	v_mov_b32_e32 v40, v30
	v_mov_b32_e32 v41, v26
	v_mov_b32_e32 v43, v28
	s_waitcnt lgkmcnt(3)
	v_mov_b32_e32 v44, v32
	s_waitcnt lgkmcnt(1)
	v_mov_b32_e32 v45, v36
	v_mov_b32_e32 v28, v25
	v_mov_b32_e32 v36, v33
	v_ashrrev_i32_e32 v25, 31, v24
	v_mov_b32_e32 v46, v34
	s_waitcnt lgkmcnt(0)
	v_mov_b32_e32 v47, v38
	v_lshlrev_b64 v[24:25], 12, v[24:25]
	v_mov_b32_e32 v26, v31
	v_mov_b32_e32 v38, v35
	v_lshl_add_u64 v[30:31], v[18:19], 0, v[24:25]
	s_add_i32 s4, s4, s98
	s_cmp_lt_i32 s4, s99
	s_waitcnt vmcnt(1)
	v_mov_b32_e32 v32, v4
	v_mov_b32_e32 v33, v6
	v_mov_b32_e32 v6, v5
	s_waitcnt vmcnt(0)
	v_mov_b32_e32 v4, v0
	v_mov_b32_e32 v5, v2
	v_mov_b32_e32 v2, v1
	v_pk_mul_f32 v[0:1], v[32:33], v[40:41]
	v_pk_mul_f32 v[24:25], v[6:7], v[42:43]
	v_pk_mul_f32 v[34:35], v[4:5], v[44:45]
	v_pk_mul_f32 v[40:41], v[2:3], v[46:47]
	v_bfe_u32 v46, v0, 16, 1
	v_pk_mul_f32 v[42:43], v[32:33], v[26:27]
	v_pk_mul_f32 v[26:27], v[6:7], v[28:29]
	v_pk_mul_f32 v[28:29], v[4:5], v[36:37]
	v_bfe_u32 v45, v24, 16, 1
	v_bfe_u32 v47, v1, 16, 1
	v_bfe_u32 v48, v34, 16, 1
	v_bfe_u32 v49, v35, 16, 1
	v_add3_u32 v0, v0, v46, s7
	v_pk_mul_f32 v[36:37], v[2:3], v[38:39]
	v_bfe_u32 v38, v41, 16, 1
	v_bfe_u32 v39, v40, 16, 1
	v_bfe_u32 v44, v25, 16, 1
	v_bfe_u32 v52, v27, 16, 1
	v_bfe_u32 v53, v26, 16, 1
	v_bfe_u32 v57, v29, 16, 1
	v_add3_u32 v24, v24, v45, s7
	v_add3_u32 v35, v35, v49, s7
	v_add3_u32 v34, v34, v48, s7
	v_add3_u32 v1, v1, v47, s7
	v_lshrrev_b32_e32 v0, 16, v0
	v_bfe_u32 v50, v37, 16, 1
	v_bfe_u32 v56, v28, 16, 1
	v_add3_u32 v25, v25, v44, s7
	v_add3_u32 v39, v40, v39, s7
	v_add3_u32 v38, v41, v38, s7
	v_add3_u32 v40, v26, v53, s7
	v_add3_u32 v41, v27, v52, s7
	v_lshrrev_b32_e32 v1, 16, v1
	v_lshrrev_b32_e32 v26, 16, v34
	v_lshrrev_b32_e32 v27, 16, v35
	v_and_or_b32 v24, v24, s8, v0
	v_add3_u32 v0, v29, v57, s7
	v_bfe_u32 v51, v36, 16, 1
	v_add3_u32 v37, v37, v50, s7
	v_and_or_b32 v27, v38, s8, v27
	v_and_or_b32 v26, v39, s8, v26
	v_and_or_b32 v25, v25, s8, v1
	v_add3_u32 v1, v28, v56, s7
	v_lshrrev_b32_e32 v0, 16, v0
	v_bfe_u32 v54, v42, 16, 1
	v_bfe_u32 v55, v43, 16, 1
	v_add3_u32 v36, v36, v51, s7
	global_store_dwordx4 v[30:31], v[24:27], off
	v_lshrrev_b32_e32 v1, 16, v1
	s_nop 0
	v_and_or_b32 v27, v37, s8, v0
	v_or_b32_e32 v0, s0, v21
	v_add3_u32 v24, v43, v55, s7
	v_add3_u32 v25, v42, v54, s7
	v_and_or_b32 v26, v36, s8, v1
	v_ashrrev_i32_e32 v1, 31, v0
	v_lshrrev_b32_e32 v28, 16, v25
	v_lshrrev_b32_e32 v24, 16, v24
	v_lshlrev_b64 v[0:1], 12, v[0:1]
	v_and_or_b32 v25, v41, s8, v24
	v_and_or_b32 v24, v40, s8, v28
	v_lshl_add_u64 v[0:1], v[18:19], 0, v[0:1]
	ds_read2_b32 v[28:29], v20 offset0:16 offset1:24
	ds_read2_b32 v[30:31], v20 offset0:82 offset1:90
	global_store_dwordx4 v[0:1], v[24:27], off
	ds_read2_b32 v[0:1], v20 offset0:49 offset1:57
	ds_read2_b32 v[34:35], v20 offset0:115 offset1:123
	ds_read2_b32 v[36:37], v20 offset0:148 offset1:156
	ds_read2_b32 v[38:39], v20 offset0:214 offset1:222
	ds_read2_b32 v[40:41], v20 offset0:181 offset1:189
	ds_read2_b32 v[42:43], v20 offset0:247 offset1:255
	s_waitcnt lgkmcnt(7)
	v_mov_b32_e32 v24, v28
	s_waitcnt lgkmcnt(5)
	v_mov_b32_e32 v26, v0
	s_waitcnt lgkmcnt(4)
	v_mov_b32_e32 v27, v34
	v_mov_b32_e32 v25, v30
	v_pk_mul_f32 v[26:27], v[6:7], v[26:27]
	s_waitcnt lgkmcnt(3)
	v_mov_b32_e32 v44, v36
	s_waitcnt lgkmcnt(2)
	v_mov_b32_e32 v45, v38
	s_waitcnt lgkmcnt(1)
	v_mov_b32_e32 v46, v40
	s_waitcnt lgkmcnt(0)
	v_mov_b32_e32 v47, v42
	v_pk_mul_f32 v[24:25], v[32:33], v[24:25]
	v_pk_mul_f32 v[44:45], v[4:5], v[44:45]
	v_pk_mul_f32 v[46:47], v[2:3], v[46:47]
	v_bfe_u32 v30, v27, 16, 1
	v_bfe_u32 v28, v46, 16, 1
	v_bfe_u32 v34, v26, 16, 1
	v_add3_u32 v30, v27, v30, s7
	v_bfe_u32 v27, v24, 16, 1
	v_bfe_u32 v36, v44, 16, 1
	v_add3_u32 v34, v26, v34, s7
	v_add3_u32 v26, v46, v28, s7
	v_bfe_u32 v28, v25, 16, 1
	v_bfe_u32 v38, v45, 16, 1
	v_add3_u32 v36, v44, v36, s7
	v_add3_u32 v24, v24, v27, s7
	v_or_b32_e32 v44, s0, v22
	v_bfe_u32 v0, v47, 16, 1
	v_add3_u32 v38, v45, v38, s7
	v_add3_u32 v25, v25, v28, s7
	v_lshrrev_b32_e32 v24, 16, v24
	v_ashrrev_i32_e32 v45, 31, v44
	v_add3_u32 v0, v47, v0, s7
	v_lshrrev_b32_e32 v25, 16, v25
	v_lshrrev_b32_e32 v28, 16, v36
	v_lshrrev_b32_e32 v27, 16, v38
	v_and_or_b32 v24, v34, s8, v24
	v_lshlrev_b64 v[44:45], 12, v[44:45]
	v_mov_b32_e32 v34, v1
	v_and_or_b32 v27, v0, s8, v27
	v_and_or_b32 v26, v26, s8, v28
	v_and_or_b32 v25, v30, s8, v25
	v_lshl_add_u64 v[44:45], v[18:19], 0, v[44:45]
	v_pk_mul_f32 v[0:1], v[6:7], v[34:35]
	v_mov_b32_e32 v38, v37
	global_store_dwordx4 v[44:45], v[24:27], off
	v_pk_mul_f32 v[4:5], v[4:5], v[38:39]
	v_mov_b32_e32 v42, v41
	v_bfe_u32 v26, v1, 16, 1
	v_pk_mul_f32 v[2:3], v[2:3], v[42:43]
	v_bfe_u32 v27, v0, 16, 1
	v_add3_u32 v1, v1, v26, s7
	v_bfe_u32 v26, v4, 16, 1
	v_mov_b32_e32 v30, v29
	v_bfe_u32 v7, v2, 16, 1
	v_add3_u32 v0, v0, v27, s7
	v_bfe_u32 v27, v5, 16, 1
	v_add3_u32 v4, v4, v26, s7
	v_pk_mul_f32 v[24:25], v[32:33], v[30:31]
	v_bfe_u32 v6, v3, 16, 1
	v_add3_u32 v2, v2, v7, s7
	v_add3_u32 v5, v5, v27, s7
	v_lshrrev_b32_e32 v4, 16, v4
	v_add3_u32 v3, v3, v6, s7
	v_bfe_u32 v6, v24, 16, 1
	v_bfe_u32 v7, v25, 16, 1
	v_lshrrev_b32_e32 v5, 16, v5
	v_and_or_b32 v2, v2, s8, v4
	v_or_b32_e32 v4, s0, v23
	v_add3_u32 v7, v25, v7, s7
	v_add3_u32 v6, v24, v6, s7
	v_and_or_b32 v3, v3, s8, v5
	v_ashrrev_i32_e32 v5, 31, v4
	v_lshrrev_b32_e32 v6, 16, v6
	v_lshrrev_b32_e32 v7, 16, v7
	v_lshlrev_b64 v[4:5], 12, v[4:5]
	v_and_or_b32 v1, v1, s8, v7
	v_and_or_b32 v0, v0, s8, v6
	v_lshl_add_u64 v[4:5], v[18:19], 0, v[4:5]
	global_store_dwordx4 v[4:5], v[0:3], off
	s_waitcnt lgkmcnt(0)
	s_cbranch_scc1 .LBB0_1343

; #define LAS __attribute__((address_space(3)))
; __device__ __forceinline__ int opaque_tid() { int t = threadIdx.x; asm volatile("" : "+v"(t)); return t; }
; __device__ __forceinline__ void conv_matrix(const float* W, int K, int ldn, int c0, int ncols, bf16_t* WT, int drow0, int mode, const float* gain, LAS unsigned char* lds) {
;     const int tid = opaque_tid(), lane = tid & 63, wave = __builtin_amdgcn_readfirstlane(tid >> 6), gw = blockIdx.x * NWAVES + wave, ngw = gridDim.x * NWAVES;
;     LAS float* scr = (LAS float*)(lds + wave * 16384);
;     const int nblk = ncols / 32, nitems = (K / 64) * nblk;
;     for (int it = gw; it < nitems; it += ngw) {
;         const int kb = it / nblk, nb = it - kb * nblk, k0 = 64 * kb, n0 = c0 + 32 * nb;
;         int drow;
;         if (mode == 1) { const int up = n0 >= FF ? 1 : 0, j = n0 - up * FF; drow = (j >> 7) * 256 + up * 128 + (j & 127); } else drow = drow0 + 32 * nb;
; #pragma unroll 8
;         for (int i = 0; i < 32; ++i) { const int kk = 2 * i + (lane >> 5); scr[kk * 33 + (lane & 31)] = W[(size_t)(k0 + kk) * ldn + n0 + (lane & 31)]; }
;         asm volatile("s_waitcnt lgkmcnt(0)" ::: "memory");
;         const int c = lane & 7;
;         f32x4 g0 = {1.f, 1.f, 1.f, 1.f}, g1 = {1.f, 1.f, 1.f, 1.f};
;         if (gain) { g0 = *(const f32x4*)(gain + k0 + 8 * c); g1 = *(const f32x4*)(gain + k0 + 8 * c + 4); }
.Lcv_p2b_top:
	s_nop 0
	v_mov_b32_e32 v1, v204
	v_readlane_b32 s68, v249, 29
	v_readfirstlane_b32 s0, v1
	s_ashr_i32 s0, s0, 6
	s_add_i32 s4, s0, s97
	v_readlane_b32 s69, v249, 30
	s_mov_b32 s98, s72
	s_movk_i32 s99, 0x1600
	s_cmp_lg_u32 s72, 0x800
	s_cbranch_scc1 .Lcv_p2b_go
	s_cmp_eq_u32 s101, 0
	s_cbranch_scc0 .Lcv_p2b_second
	s_movk_i32 s99, 2048
	s_branch .Lcv_p2b_go
.Lcv_p2b_second:
	s_add_i32 s4, s4, 1536
	s_movk_i32 s98, 0x600
.Lcv_p2b_go:
	s_cmp_ge_i32 s4, s99
	s_cbranch_scc1 .Lcv_p2b_exit
	v_lshlrev_b32_e32 v2, 2, v1
	v_readlane_b32 s16, v249, 8
	s_lshl_b32 s0, s0, 14
	v_and_b32_e32 v6, 0x7c, v2
	v_mov_b32_e32 v7, 0
	v_readlane_b32 s17, v249, 9
	s_add_i32 s2, s0, 0
	s_mov_b64 s[0:1], 0x2c00000
	v_lshl_add_u64 v[2:3], s[16:17], 0, v[6:7]
	v_lshl_add_u64 v[2:3], v[2:3], 0, s[0:1]
	v_and_b32_e32 v5, 7, v1
	v_bfe_u32 v11, v1, 3, 3
	v_readlane_b32 s0, v249, 24
	v_bfe_u32 v0, v1, 5, 1
	v_add_u32_e32 v4, s2, v6
	v_mul_u32_u24_e32 v1, 0x420, v5
	v_lshlrev_b32_e32 v6, 4, v5
	v_readlane_b32 s1, v249, 25
	v_lshlrev_b32_e32 v5, 2, v11
	v_add3_u32 v12, s2, v1, v5
	v_lshl_add_u64 v[6:7], s[0:1], 0, v[6:7]
	v_or_b32_e32 v13, 8, v11
	v_or_b32_e32 v14, 16, v11
	v_or_b32_e32 v15, 24, v11
	v_mov_b32_e32 v1, v0
	s_movk_i32 s5, 0x84
	s_movk_i32 s6, 0x7fff
	s_mov_b32 s7, 0xffff0000
	s_movk_i32 s8, 0x2c00
	v_readlane_b32 s18, v249, 10
	v_readlane_b32 s19, v249, 11
	v_readlane_b32 s20, v249, 12
	v_readlane_b32 s21, v249, 13
	v_readlane_b32 s22, v249, 14
	v_readlane_b32 s23, v249, 15
	v_readlane_b32 s24, v249, 16
	v_readlane_b32 s25, v249, 17
	v_readlane_b32 s26, v249, 18
	v_readlane_b32 s27, v249, 19
	v_readlane_b32 s28, v249, 20
	v_readlane_b32 s29, v249, 21
	v_readlane_b32 s30, v249, 22
	v_readlane_b32 s31, v249, 23

; __device__ __forceinline__ void conv_matrix(const float* W, int K, int ldn, int c0, int ncols, bf16_t* WT, int drow0, int mode, const float* gain, LAS unsigned char* lds) {
;     ...
; #pragma unroll 8
;         for (int i = 0; i < 32; ++i) { const int kk = 2 * i + (lane >> 5); scr[kk * 33 + (lane & 31)] = W[(size_t)(k0 + kk) * ldn + n0 + (lane & 31)]; }
.LBB0_1349:
	s_lshl_b32 s10, s9, 1
	s_lshl_b32 s11, s3, 1
	v_or_b32_e32 v18, s11, v10
	s_add_i32 s14, s10, 4
	s_add_i32 s15, s11, 4
	s_add_i32 s16, s10, 8
	s_add_i32 s17, s11, 8
	s_add_i32 s18, s10, 12
	s_add_i32 s19, s11, 12
	s_add_i32 s20, s10, 16
	s_add_i32 s21, s11, 16
	s_add_i32 s22, s10, 20
	s_add_i32 s23, s11, 20
	s_add_i32 s24, s10, 24
	s_add_i32 s25, s11, 24
	s_add_i32 s26, s10, 28
	s_add_i32 s27, s11, 28
	v_or_b32_e32 v16, s10, v5
	v_ashrrev_i32_e32 v19, 31, v18
	v_or_b32_e32 v20, s14, v5
	v_or_b32_e32 v22, s15, v10
	v_or_b32_e32 v24, s16, v5
	v_or_b32_e32 v26, s17, v10
	v_or_b32_e32 v28, s18, v5
	v_or_b32_e32 v30, s19, v10
	v_or_b32_e32 v32, s20, v5
	v_or_b32_e32 v34, s21, v10
	v_or_b32_e32 v36, s22, v5
	v_or_b32_e32 v38, s23, v10
	v_or_b32_e32 v40, s24, v5
	v_or_b32_e32 v42, s25, v10
	v_or_b32_e32 v44, s26, v5
	v_or_b32_e32 v46, s27, v10
	v_ashrrev_i32_e32 v17, 31, v16
	v_lshlrev_b64 v[18:19], 13, v[18:19]
	v_ashrrev_i32_e32 v23, 31, v22
	v_ashrrev_i32_e32 v21, 31, v20
	v_ashrrev_i32_e32 v27, 31, v26
	v_ashrrev_i32_e32 v25, 31, v24
	v_ashrrev_i32_e32 v31, 31, v30
	v_ashrrev_i32_e32 v29, 31, v28
	v_ashrrev_i32_e32 v35, 31, v34
	v_ashrrev_i32_e32 v33, 31, v32
	v_ashrrev_i32_e32 v39, 31, v38
	v_ashrrev_i32_e32 v37, 31, v36
	v_ashrrev_i32_e32 v43, 31, v42
	v_ashrrev_i32_e32 v41, 31, v40
	v_ashrrev_i32_e32 v47, 31, v46
	v_ashrrev_i32_e32 v45, 31, v44
	v_lshlrev_b64 v[16:17], 13, v[16:17]
	v_lshl_add_u64 v[18:19], v[8:9], 0, v[18:19]
	v_lshlrev_b64 v[20:21], 13, v[20:21]
	v_lshlrev_b64 v[22:23], 13, v[22:23]
	v_lshlrev_b64 v[24:25], 13, v[24:25]
	v_lshlrev_b64 v[26:27], 13, v[26:27]
	v_lshlrev_b64 v[28:29], 13, v[28:29]
	v_lshlrev_b64 v[30:31], 13, v[30:31]
	v_lshlrev_b64 v[32:33], 13, v[32:33]
	v_lshlrev_b64 v[34:35], 13, v[34:35]
	v_lshlrev_b64 v[36:37], 13, v[36:37]
	v_lshlrev_b64 v[38:39], 13, v[38:39]
	v_lshlrev_b64 v[40:41], 13, v[40:41]
	v_lshlrev_b64 v[42:43], 13, v[42:43]
	v_lshlrev_b64 v[44:45], 13, v[44:45]
	v_lshlrev_b64 v[46:47], 13, v[46:47]
	v_lshl_add_u64 v[16:17], v[8:9], 0, v[16:17]
	v_lshl_add_u64 v[22:23], v[8:9], 0, v[22:23]
	v_lshl_add_u64 v[20:21], v[8:9], 0, v[20:21]
	v_lshl_add_u64 v[26:27], v[8:9], 0, v[26:27]
	v_lshl_add_u64 v[24:25], v[8:9], 0, v[24:25]
	v_lshl_add_u64 v[30:31], v[8:9], 0, v[30:31]
	v_lshl_add_u64 v[28:29], v[8:9], 0, v[28:29]
	v_lshl_add_u64 v[34:35], v[8:9], 0, v[34:35]
	v_lshl_add_u64 v[32:33], v[8:9], 0, v[32:33]
	v_lshl_add_u64 v[38:39], v[8:9], 0, v[38:39]
	v_lshl_add_u64 v[36:37], v[8:9], 0, v[36:37]
	v_lshl_add_u64 v[42:43], v[8:9], 0, v[42:43]
	v_lshl_add_u64 v[40:41], v[8:9], 0, v[40:41]
	v_lshl_add_u64 v[46:47], v[8:9], 0, v[46:47]
	v_lshl_add_u64 v[44:45], v[8:9], 0, v[44:45]
	global_load_dword v48, v[18:19], off
	global_load_dword v49, v[16:17], off
	global_load_dword v50, v[22:23], off
	global_load_dword v51, v[20:21], off
	global_load_dword v52, v[26:27], off
	global_load_dword v53, v[24:25], off
	global_load_dword v54, v[30:31], off
	global_load_dword v55, v[28:29], off
	global_load_dword v56, v[34:35], off
	global_load_dword v57, v[32:33], off
	global_load_dword v58, v[38:39], off
	global_load_dword v59, v[36:37], off
	global_load_dword v60, v[42:43], off
	global_load_dword v61, v[40:41], off
	global_load_dword v62, v[46:47], off
	global_load_dword v63, v[44:45], off
	v_or_b32_e32 v18, s10, v1
	v_or_b32_e32 v16, s11, v0
	s_add_i32 s3, s3, 16
	s_add_i32 s9, s9, 16
	s_add_i32 s1, s1, -16
	v_mad_u64_u32 v[16:17], s[10:11], v16, s5, v[4:5]
	v_mad_u64_u32 v[18:19], s[10:11], v18, s5, v[4:5]
	v_or_b32_e32 v17, s14, v1
	v_or_b32_e32 v19, s15, v0
	v_or_b32_e32 v26, s16, v1
	v_or_b32_e32 v24, s17, v0
	v_or_b32_e32 v30, s18, v1
	v_or_b32_e32 v28, s19, v0
	v_or_b32_e32 v34, s20, v1
	v_or_b32_e32 v32, s21, v0
	v_or_b32_e32 v38, s22, v1
	v_or_b32_e32 v36, s23, v0
	v_or_b32_e32 v42, s24, v1
	v_or_b32_e32 v40, s25, v0
	v_or_b32_e32 v46, s26, v1
	v_or_b32_e32 v44, s27, v0
	s_cmp_lg_u32 s1, 0
	v_mad_u64_u32 v[20:21], s[10:11], v19, s5, v[4:5]
	v_mad_u64_u32 v[22:23], s[10:11], v17, s5, v[4:5]
	v_mad_u64_u32 v[24:25], s[10:11], v24, s5, v[4:5]
	v_mad_u64_u32 v[26:27], s[10:11], v26, s5, v[4:5]
	v_mad_u64_u32 v[28:29], s[10:11], v28, s5, v[4:5]
	v_mad_u64_u32 v[30:31], s[10:11], v30, s5, v[4:5]
	v_mad_u64_u32 v[32:33], s[10:11], v32, s5, v[4:5]
	v_mad_u64_u32 v[34:35], s[10:11], v34, s5, v[4:5]
	v_mad_u64_u32 v[36:37], s[10:11], v36, s5, v[4:5]
	v_mad_u64_u32 v[38:39], s[10:11], v38, s5, v[4:5]
	v_mad_u64_u32 v[40:41], s[10:11], v40, s5, v[4:5]
	v_mad_u64_u32 v[42:43], s[10:11], v42, s5, v[4:5]
	v_mad_u64_u32 v[44:45], s[10:11], v44, s5, v[4:5]
	v_mad_u64_u32 v[46:47], s[10:11], v46, s5, v[4:5]
	s_waitcnt vmcnt(15)
	ds_write_b32 v16, v48
	s_waitcnt vmcnt(14)
	ds_write_b32 v18, v49
	s_waitcnt vmcnt(13)
	ds_write_b32 v20, v50
	s_waitcnt vmcnt(12)
	ds_write_b32 v22, v51
	s_waitcnt vmcnt(11)
	ds_write_b32 v24, v52
	s_waitcnt vmcnt(10)
	ds_write_b32 v26, v53
	s_waitcnt vmcnt(9)
	ds_write_b32 v28, v54
	s_waitcnt vmcnt(8)
	ds_write_b32 v30, v55
	s_waitcnt vmcnt(7)
	ds_write_b32 v32, v56
	s_waitcnt vmcnt(6)
	ds_write_b32 v34, v57
	s_waitcnt vmcnt(5)
	ds_write_b32 v36, v58
	s_waitcnt vmcnt(4)
	ds_write_b32 v38, v59
	s_waitcnt vmcnt(3)
	ds_write_b32 v40, v60
	s_waitcnt vmcnt(2)
	ds_write_b32 v42, v61
	s_waitcnt vmcnt(1)
	ds_write_b32 v44, v62
	s_waitcnt vmcnt(0)
	ds_write_b32 v46, v63
	s_cbranch_scc1 .LBB0_1349
; #define LAS __attribute__((address_space(3)))
; __device__ __forceinline__ unsigned pk2(float lo, float hi) { return f2bf(lo) | (f2bf(hi) << 16); }
; __device__ __forceinline__ void conv_matrix(const float* W, int K, int ldn, int c0, int ncols, bf16_t* WT, int drow0, int mode, const float* gain, LAS unsigned char* lds) {
;     ...
;         for (int j = 0; j < 4; ++j) { const int n = (lane >> 3) + 8 * j; const LAS float* s = scr + (8 * c) * 33 + n;
;             u32x4 o; o.x = pk2(s[0 * 33] * g0.x, s[1 * 33] * g0.y); o.y = pk2(s[2 * 33] * g0.z, s[3 * 33] * g0.w); o.z = pk2(s[4 * 33] * g1.x, s[5 * 33] * g1.y); o.w = pk2(s[6 * 33] * g1.z, s[7 * 33] * g1.w);
;             *(u32x4*)(WT + (size_t)(drow + n) * K + k0 + 8 * c) = o; }
;         asm volatile("s_waitcnt lgkmcnt(0)" ::: "memory");
;     }
	s_waitcnt lgkmcnt(0)
	ds_read2_b32 v[8:9], v12 offset1:8
	ds_read2_b32 v[22:23], v12 offset0:33 offset1:41
	ds_read2_b32 v[24:25], v12 offset0:66 offset1:74
	ds_read2_b32 v[26:27], v12 offset0:99 offset1:107
	ds_read2_b32 v[28:29], v12 offset0:132 offset1:140
	ds_read2_b32 v[30:31], v12 offset0:165 offset1:173
	s_waitcnt lgkmcnt(5)
	v_bfe_u32 v5, v8, 16, 1
	v_add3_u32 v5, v8, v5, s6
	s_waitcnt lgkmcnt(4)
	v_bfe_u32 v8, v22, 16, 1
	v_lshrrev_b32_e32 v5, 16, v5
	v_add3_u32 v8, v22, v8, s6
	v_and_or_b32 v16, v8, s7, v5
	s_waitcnt lgkmcnt(3)
	v_bfe_u32 v5, v24, 16, 1
	v_add3_u32 v5, v24, v5, s6
	s_waitcnt lgkmcnt(2)
	v_bfe_u32 v8, v26, 16, 1
	ds_read2_b32 v[32:33], v12 offset0:198 offset1:206
	v_lshrrev_b32_e32 v5, 16, v5
	v_add3_u32 v8, v26, v8, s6
	ds_read2_b32 v[34:35], v12 offset0:231 offset1:239
	v_and_or_b32 v17, v8, s7, v5
	s_waitcnt lgkmcnt(3)
	v_bfe_u32 v5, v28, 16, 1
	v_add3_u32 v5, v28, v5, s6
	s_waitcnt lgkmcnt(2)
	v_bfe_u32 v8, v30, 16, 1
	v_lshrrev_b32_e32 v5, 16, v5
	v_add3_u32 v8, v30, v8, s6
	v_and_or_b32 v18, v8, s7, v5
	s_waitcnt lgkmcnt(1)
	v_bfe_u32 v5, v32, 16, 1
	v_add3_u32 v5, v32, v5, s6
	s_waitcnt lgkmcnt(0)
	v_bfe_u32 v8, v34, 16, 1
	s_ashr_i32 s3, s2, 31
	v_lshrrev_b32_e32 v5, 16, v5
	v_add3_u32 v8, v34, v8, s6
	v_lshl_add_u64 v[20:21], s[2:3], 1, v[6:7]
	v_and_or_b32 v19, v8, s7, v5
	v_or_b32_e32 v5, s0, v11
	v_mad_i64_i32 v[36:37], s[2:3], v5, s8, v[20:21]
	v_bfe_u32 v5, v9, 16, 1
	v_add3_u32 v5, v9, v5, s6
	v_bfe_u32 v8, v23, 16, 1
	v_lshrrev_b32_e32 v5, 16, v5
	v_add3_u32 v8, v23, v8, s6
	global_store_dwordx4 v[36:37], v[16:19], off
	s_add_i32 s4, s4, s98
	s_cmp_lt_i32 s4, s99
	v_and_or_b32 v16, v8, s7, v5
	v_bfe_u32 v5, v25, 16, 1
	v_add3_u32 v5, v25, v5, s6
	v_bfe_u32 v8, v27, 16, 1
	v_lshrrev_b32_e32 v5, 16, v5
	v_add3_u32 v8, v27, v8, s6
	v_and_or_b32 v17, v8, s7, v5
	v_bfe_u32 v5, v29, 16, 1
	v_add3_u32 v5, v29, v5, s6
	v_bfe_u32 v8, v31, 16, 1
	v_lshrrev_b32_e32 v5, 16, v5
	v_add3_u32 v8, v31, v8, s6
	v_and_or_b32 v18, v8, s7, v5
	v_bfe_u32 v5, v33, 16, 1
	v_add3_u32 v5, v33, v5, s6
	v_bfe_u32 v8, v35, 16, 1
	v_lshrrev_b32_e32 v5, 16, v5
	v_add3_u32 v8, v35, v8, s6
	v_and_or_b32 v19, v8, s7, v5
	v_or_b32_e32 v5, s0, v13
	ds_read2_b32 v[8:9], v12 offset0:16 offset1:24
	v_mad_i64_i32 v[22:23], s[2:3], v5, s8, v[20:21]
	global_store_dwordx4 v[22:23], v[16:19], off
	ds_read2_b32 v[22:23], v12 offset0:49 offset1:57
	ds_read2_b32 v[24:25], v12 offset0:82 offset1:90
	ds_read2_b32 v[26:27], v12 offset0:115 offset1:123
	s_waitcnt lgkmcnt(3)
	v_bfe_u32 v5, v8, 16, 1
	v_add3_u32 v5, v8, v5, s6
	s_waitcnt lgkmcnt(2)
	v_bfe_u32 v8, v22, 16, 1
	ds_read2_b32 v[28:29], v12 offset0:148 offset1:156
	v_lshrrev_b32_e32 v5, 16, v5
	v_add3_u32 v8, v22, v8, s6
	ds_read2_b32 v[30:31], v12 offset0:181 offset1:189
	v_and_or_b32 v16, v8, s7, v5
	s_waitcnt lgkmcnt(3)
	v_bfe_u32 v5, v24, 16, 1
	v_add3_u32 v5, v24, v5, s6
	s_waitcnt lgkmcnt(2)
	v_bfe_u32 v8, v26, 16, 1
	ds_read2_b32 v[32:33], v12 offset0:214 offset1:222
	v_lshrrev_b32_e32 v5, 16, v5
	v_add3_u32 v8, v26, v8, s6
	ds_read2_b32 v[34:35], v12 offset0:247 offset1:255
	v_and_or_b32 v17, v8, s7, v5
	s_waitcnt lgkmcnt(3)
	v_bfe_u32 v5, v28, 16, 1
	v_add3_u32 v5, v28, v5, s6
	s_waitcnt lgkmcnt(2)
	v_bfe_u32 v8, v30, 16, 1
	v_lshrrev_b32_e32 v5, 16, v5
	v_add3_u32 v8, v30, v8, s6
	v_and_or_b32 v18, v8, s7, v5
	s_waitcnt lgkmcnt(1)
	v_bfe_u32 v5, v32, 16, 1
	v_add3_u32 v5, v32, v5, s6
	s_waitcnt lgkmcnt(0)
	v_bfe_u32 v8, v34, 16, 1
	v_lshrrev_b32_e32 v5, 16, v5
	v_add3_u32 v8, v34, v8, s6
	v_and_or_b32 v19, v8, s7, v5
	v_or_b32_e32 v5, s0, v14
	v_mad_i64_i32 v[36:37], s[2:3], v5, s8, v[20:21]
	v_bfe_u32 v5, v9, 16, 1
	v_add3_u32 v5, v9, v5, s6
	v_bfe_u32 v8, v23, 16, 1
	v_lshrrev_b32_e32 v5, 16, v5
	v_add3_u32 v8, v23, v8, s6
	global_store_dwordx4 v[36:37], v[16:19], off
	s_nop 1
	v_and_or_b32 v16, v8, s7, v5
	v_bfe_u32 v5, v25, 16, 1
	v_add3_u32 v5, v25, v5, s6
	v_bfe_u32 v8, v27, 16, 1
	v_lshrrev_b32_e32 v5, 16, v5
	v_add3_u32 v8, v27, v8, s6
	v_and_or_b32 v17, v8, s7, v5
	v_bfe_u32 v5, v29, 16, 1
	v_add3_u32 v5, v29, v5, s6
	v_bfe_u32 v8, v31, 16, 1
	v_lshrrev_b32_e32 v5, 16, v5
	v_add3_u32 v8, v31, v8, s6
	v_and_or_b32 v18, v8, s7, v5
	v_bfe_u32 v5, v33, 16, 1
	v_add3_u32 v5, v33, v5, s6
	v_bfe_u32 v8, v35, 16, 1
	v_lshrrev_b32_e32 v5, 16, v5
	v_add3_u32 v8, v35, v8, s6
	v_and_or_b32 v19, v8, s7, v5
	v_or_b32_e32 v5, s0, v15
	v_mad_i64_i32 v[8:9], s[0:1], v5, s8, v[20:21]
	global_store_dwordx4 v[8:9], v[16:19], off
	s_waitcnt lgkmcnt(0)
	s_cbranch_scc1 .LBB0_1348

; #define LAS __attribute__((address_space(3)))
; #define SBAR() __builtin_amdgcn_sched_barrier(0)
; __device__ __forceinline__ void qkt(f32x16& p0, f32x16& p1, const LAS unsigned char* Kb, int r32, int hi, const bf16x8* qr, const f32x16& negm) {
;     const LAS unsigned char* kb[4];
; #pragma unroll
;     for (int dd = 0; dd < 4; ++dd) kb[dd] = Kb + kswz(r32, dd * 32 + hi * 16);
;     ...
;     bf16x8 fa[12], fb[12];
;     fa[0] = LDK(0, 0); fb[0] = LDK(0, 1); fa[1] = LDK(1, 0); fb[1] = LDK(1, 1);
;     __builtin_amdgcn_s_setprio(1);
; #pragma unroll
;     for (int d0 = 0; d0 < 12; ++d0) {
;         if (d0 + 2 < 12) { fa[d0 + 2] = LDK(d0 + 2, 0); fb[d0 + 2] = LDK(d0 + 2, 1); }
;         SBAR();
;         p0 = __builtin_amdgcn_mfma_f32_32x32x16_bf16(fa[d0], qr[d0], d0 == 0 ? negm : p0, 0, 0, 0);
;         p1 = __builtin_amdgcn_mfma_f32_32x32x16_bf16(fb[d0], qr[d0], d0 == 0 ? negm : p1, 0, 0, 0);
;         SBAR();
;     }
;     __builtin_amdgcn_s_setprio(0);
;     ...
; }
.LBB0_1609:
	s_cmp_gt_i32 s53, s52
	s_cbranch_scc1 .LBB0_1618
	s_mul_i32 s0, s70, 0x6000
	v_add_u32_e32 v116, s0, v211
	v_add_u32_e32 v244, v116, v212
	v_add_u32_e32 v245, v116, v213
	ds_read_b128 v[112:115], v244 offset:49152
	ds_read_b128 v[220:223], v244 offset:61440
	ds_read_b128 v[224:227], v245 offset:49152
	ds_read_b128 v[228:231], v245 offset:61440
	v_add_u32_e32 v246, v116, v214
	v_add_u32_e32 v247, v116, v215
	s_setprio 1
	ds_read_b128 v[232:235], v246 offset:49152
	ds_read_b128 v[236:239], v246 offset:61440
	s_waitcnt lgkmcnt(4)
	v_mfma_f32_32x32x16_bf16 v[128:143], v[112:115], v[144:147], v[96:111]
	v_mfma_f32_32x32x16_bf16 v[112:127], v[220:223], v[144:147], v[96:111]
	ds_read_b128 v[220:223], v247 offset:49152
	ds_read_b128 v[240:243], v247 offset:61440
	s_waitcnt lgkmcnt(4)
	v_mfma_f32_32x32x16_bf16 v[128:143], v[224:227], v[148:151], v[128:143]
	v_mfma_f32_32x32x16_bf16 v[112:127], v[228:231], v[148:151], v[112:127]
	ds_read_b128 v[224:227], v244 offset:49280
	ds_read_b128 v[228:231], v244 offset:61568
	s_waitcnt lgkmcnt(4)
	v_mfma_f32_32x32x16_bf16 v[128:143], v[232:235], v[152:155], v[128:143]
	v_mfma_f32_32x32x16_bf16 v[112:127], v[236:239], v[152:155], v[112:127]
	ds_read_b128 v[232:235], v245 offset:49280
	ds_read_b128 v[236:239], v245 offset:61568
	s_waitcnt lgkmcnt(4)
	v_mfma_f32_32x32x16_bf16 v[128:143], v[220:223], v[156:159], v[128:143]
	v_mfma_f32_32x32x16_bf16 v[112:127], v[240:243], v[156:159], v[112:127]
	ds_read_b128 v[220:223], v246 offset:49280
	ds_read_b128 v[240:243], v246 offset:61568
	s_waitcnt lgkmcnt(4)
	v_mfma_f32_32x32x16_bf16 v[128:143], v[224:227], v[160:163], v[128:143]
	v_mfma_f32_32x32x16_bf16 v[112:127], v[228:231], v[160:163], v[112:127]
	ds_read_b128 v[224:227], v247 offset:49280
	ds_read_b128 v[228:231], v247 offset:61568
	s_waitcnt lgkmcnt(4)
	v_mfma_f32_32x32x16_bf16 v[128:143], v[232:235], v[164:167], v[128:143]
	v_mfma_f32_32x32x16_bf16 v[112:127], v[236:239], v[164:167], v[112:127]
	ds_read_b128 v[232:235], v244 offset:49408
	ds_read_b128 v[236:239], v244 offset:61696
	s_waitcnt lgkmcnt(4)
	v_mfma_f32_32x32x16_bf16 v[128:143], v[220:223], v[168:171], v[128:143]
	v_mfma_f32_32x32x16_bf16 v[112:127], v[240:243], v[168:171], v[112:127]
	ds_read_b128 v[220:223], v245 offset:49408
	ds_read_b128 v[240:243], v245 offset:61696
	s_waitcnt lgkmcnt(4)
	v_mfma_f32_32x32x16_bf16 v[128:143], v[224:227], v[172:175], v[128:143]
	v_mfma_f32_32x32x16_bf16 v[112:127], v[228:231], v[172:175], v[112:127]
	ds_read_b128 v[224:227], v246 offset:49408
	ds_read_b128 v[228:231], v246 offset:61696
	s_waitcnt lgkmcnt(4)
	v_mfma_f32_32x32x16_bf16 v[128:143], v[232:235], v[176:179], v[128:143]
	v_mfma_f32_32x32x16_bf16 v[112:127], v[236:239], v[176:179], v[112:127]
	ds_read_b128 v[232:235], v247 offset:49408
	ds_read_b128 v[236:239], v247 offset:61696
	s_waitcnt lgkmcnt(4)
	v_mfma_f32_32x32x16_bf16 v[128:143], v[220:223], v[180:183], v[128:143]
	v_mfma_f32_32x32x16_bf16 v[112:127], v[240:243], v[180:183], v[112:127]
	s_waitcnt lgkmcnt(2)
	v_mfma_f32_32x32x16_bf16 v[128:143], v[224:227], v[184:187], v[128:143]
	v_mfma_f32_32x32x16_bf16 v[112:127], v[228:231], v[184:187], v[112:127]
	s_waitcnt lgkmcnt(0)
	v_mfma_f32_32x32x16_bf16 v[128:143], v[232:235], v[188:191], v[128:143]
	v_mfma_f32_32x32x16_bf16 v[112:127], v[236:239], v[188:191], v[112:127]
	s_setprio 0
	s_add_i32 s0, s53, 63
	s_cmp_le_i32 s0, s86
	s_cbranch_scc1 .LBB0_1612
; __device__ __forceinline__ void mask_tile(f32x16& p0, f32x16& p1, int dq) {
;     const float NEG = -__builtin_inff();
; #pragma unroll
;     for (int r = 0; r < 16; ++r) { const int c = (r & 3) + 8 * (r >> 2);
;         if (dq - c < 0) p0[r] = NEG;
;         if (dq - c - 32 < 0) p1[r] = NEG; }
; }
	v_cmp_gt_i32_e64 s[66:67], 26, v218
	v_cmp_gt_i32_e64 s[68:69], 27, v218
	v_cmp_gt_i32_e64 s[64:65], 25, v218
	s_and_b64 s[66:67], s[68:69], s[66:67]
	v_cmp_gt_i32_e64 s[62:63], 24, v218
	s_and_b64 s[64:65], s[66:67], s[64:65]
	v_cmp_gt_i32_e64 s[60:61], 19, v218
	s_and_b64 s[62:63], s[64:65], s[62:63]
	v_cmp_gt_i32_e64 s[58:59], 18, v218
	s_and_b64 s[60:61], s[62:63], s[60:61]
	v_cmp_gt_i32_e64 s[56:57], 17, v218
	s_and_b64 s[58:59], s[60:61], s[58:59]
	v_cmp_gt_i32_e64 s[54:55], 16, v218
	s_and_b64 s[56:57], s[58:59], s[56:57]
	v_cmp_gt_i32_e64 s[50:51], 11, v218
	s_and_b64 s[54:55], s[56:57], s[54:55]
	v_cmp_gt_i32_e64 s[48:49], 10, v218
	s_and_b64 s[50:51], s[54:55], s[50:51]
	v_cmp_gt_i32_e64 s[46:47], 9, v218
	s_and_b64 s[48:49], s[50:51], s[48:49]
	v_cmp_gt_i32_e64 s[44:45], 8, v218
	s_and_b64 s[46:47], s[48:49], s[46:47]
	v_cmp_gt_i32_e64 s[42:43], 3, v218
	s_and_b64 s[44:45], s[46:47], s[44:45]
	v_cmp_gt_i32_e64 s[40:41], 2, v218
	s_and_b64 s[42:43], s[44:45], s[42:43]
	v_cmp_gt_i32_e64 s[38:39], 1, v218
	s_and_b64 s[40:41], s[42:43], s[40:41]
	v_cmp_gt_i32_e64 s[36:37], 0, v218
	s_and_b64 s[38:39], s[40:41], s[38:39]
	s_and_b64 s[36:37], s[38:39], s[36:37]
	v_cmp_gt_i32_e64 s[34:35], 58, v218
	v_cndmask_b32_e64 v128, v128, v207, s[36:37]
	v_cmp_gt_i32_e64 s[36:37], 59, v218
	v_cmp_gt_i32_e64 s[30:31], 57, v218
	s_and_b64 s[34:35], s[36:37], s[34:35]
	v_cmp_gt_i32_e64 s[28:29], 56, v218
	s_and_b64 s[30:31], s[34:35], s[30:31]
	v_cmp_gt_i32_e64 s[26:27], 51, v218
	s_and_b64 s[28:29], s[30:31], s[28:29]
	v_cmp_gt_i32_e64 s[24:25], 50, v218
	s_and_b64 s[26:27], s[28:29], s[26:27]
	v_cmp_gt_i32_e64 s[22:23], 49, v218
	s_and_b64 s[24:25], s[26:27], s[24:25]
	v_cmp_gt_i32_e64 s[20:21], 48, v218
	s_and_b64 s[22:23], s[24:25], s[22:23]
	v_cmp_gt_i32_e64 s[18:19], 43, v218
	s_and_b64 s[20:21], s[22:23], s[20:21]
	v_cmp_gt_i32_e64 s[16:17], 42, v218
	s_and_b64 s[18:19], s[20:21], s[18:19]
	v_cmp_gt_i32_e64 s[14:15], 41, v218
	s_and_b64 s[16:17], s[18:19], s[16:17]
	v_cmp_gt_i32_e64 s[12:13], 40, v218
	s_and_b64 s[14:15], s[16:17], s[14:15]
	v_cmp_gt_i32_e64 s[10:11], 35, v218
	s_and_b64 s[12:13], s[14:15], s[12:13]
	v_cmp_gt_i32_e64 s[8:9], 34, v218
	s_and_b64 s[10:11], s[12:13], s[10:11]
	v_cmp_gt_i32_e64 s[0:1], 33, v218
	s_and_b64 s[8:9], s[10:11], s[8:9]
	v_cmp_gt_i32_e32 vcc, 32, v218
	s_and_b64 s[0:1], s[8:9], s[0:1]
	s_and_b64 vcc, s[0:1], vcc
	v_cndmask_b32_e64 v143, v143, v207, s[68:69]
	v_cndmask_b32_e64 v142, v142, v207, s[66:67]
	v_cndmask_b32_e64 v141, v141, v207, s[64:65]
	v_cndmask_b32_e64 v140, v140, v207, s[62:63]
	v_cndmask_b32_e64 v139, v139, v207, s[60:61]
	v_cndmask_b32_e64 v138, v138, v207, s[58:59]
	v_cndmask_b32_e64 v137, v137, v207, s[56:57]
	v_cndmask_b32_e64 v136, v136, v207, s[54:55]
	v_cndmask_b32_e64 v135, v135, v207, s[50:51]
	v_cndmask_b32_e64 v134, v134, v207, s[48:49]
	v_cndmask_b32_e64 v133, v133, v207, s[46:47]
	v_cndmask_b32_e64 v132, v132, v207, s[44:45]
	v_cndmask_b32_e64 v131, v131, v207, s[42:43]
	v_cndmask_b32_e64 v130, v130, v207, s[40:41]
	v_cndmask_b32_e64 v129, v129, v207, s[38:39]
	v_cndmask_b32_e64 v127, v127, v207, s[36:37]
	v_cndmask_b32_e64 v126, v126, v207, s[34:35]
	v_cndmask_b32_e64 v125, v125, v207, s[30:31]
	v_cndmask_b32_e64 v124, v124, v207, s[28:29]
	v_cndmask_b32_e64 v123, v123, v207, s[26:27]
	v_cndmask_b32_e64 v122, v122, v207, s[24:25]
	v_cndmask_b32_e64 v121, v121, v207, s[22:23]
	v_cndmask_b32_e64 v120, v120, v207, s[20:21]
	v_cndmask_b32_e64 v119, v119, v207, s[18:19]
	v_cndmask_b32_e64 v118, v118, v207, s[16:17]
	v_cndmask_b32_e64 v117, v117, v207, s[14:15]
	v_cndmask_b32_e64 v116, v116, v207, s[12:13]
	v_cndmask_b32_e64 v115, v115, v207, s[10:11]
	v_cndmask_b32_e64 v114, v114, v207, s[8:9]
	v_cndmask_b32_e64 v113, v113, v207, s[0:1]
	v_cndmask_b32_e32 v112, v112, v207, vcc
